# GEMM tail overlap: PH4/PH7 main pass covers M-tiles 0..255 (4 exact rounds), grid barrier, then the 8 tiles of M-tiles 256/257 run on WGs 0-7 concurrently with the next rmsnorm-residual pass on the ot
# speedup vs baseline: 1.0098x; 1.0080x over previous
; template <class Epi, class Sched, bool ALIGN_EPI = false, bool SP2 = false>
; __device__ __forceinline__ void gemm_phase(PG8_LAS unsigned char* lds, const Gemm g, const Sched& S, const Epi& E) {
;     ...
;     const int wid = __builtin_amdgcn_readfirstlane(tid >> 6), lane = tid & 63, wr = wid >> 2, wc = wid & 3, fr = lane & 15, fq = lane >> 4;
;     int K = g.K; asm volatile("" : "+s"(K));
;     const int nt = K / BK;
;     unsigned voffA[2], voffB[2];
; #pragma unroll
;     for (int i = 0; i < 2; ++i) { int R, C; stage_rc(tid * 16 + i * 8192, R, C); const int Rb = Epi::PERM ? ((R & ~31) + perm32(R & 31)) : R;
;         voffA[i] = (unsigned)(R * g.lda + C) * 2u; voffB[i] = (unsigned)(Rb * K + C) * 2u; }
;     const size_t kstep = (size_t)(BK * 2);
;     const size_t hstepA = (size_t)HALF * g.lda * 2, hstepB = (size_t)HALF * K * 2;
;     const size_t tstepA = 2 * hstepA, tstepB = 2 * hstepB;
;     const unsigned ldsw = (unsigned)wid * 1024u;
;     const int aoff = lds_byte(wr * 64 + fr, fq * 8), boff = lds_byte(wc * 32 + fr, fq * 8);
;     ...
;     Unit cur, nxt; int ui = 0;
;     if (!S.next(0, cur)) return;
;     f32x4 acc[2][2][4][2];
; #pragma unroll
;     for (int a = 0; a < 2; ++a)
; #pragma unroll
;         for (int b = 0; b < 2; ++b)
; #pragma unroll
;             for (int m = 0; m < 4; ++m)
; #pragma unroll
;                 for (int n = 0; n < 2; ++n) acc[a][b][m][n] = (f32x4){0.f, 0.f, 0.f, 0.f};
;     bf16x8 At[4][2], B0[2][2], B1[2][2];
;     const char* cA = (cur.pm < g.pm_split) ? (const char*)g.A + (size_t)cur.pm * tstepA : (const char*)g.A2 + (size_t)(cur.pm - g.pm_split) * tstepA; const char* cB = (const char*)g.Bt + (size_t)cur.pn * tstepB;
;     S.a_ready(cur);
;     if constexpr (SP2) {
;         PG8_STAGE(PG8_SB(0, 0), cB, voffB); PG8_STAGE(PG8_SB(0, 1), cB + hstepB, voffB); PG8_STAGE(PG8_SA(0, 0), cA, voffA); PG8_STAGE(PG8_SA(0, 1), cA + hstepA, voffA);
;         if (wr == 1) PG8_BAR;
;         PG8_WAIT_V(2); PG8_BAR;
;         PG8_STAGE(PG8_SB(1, 0), cB + kstep, voffB); PG8_STAGE(PG8_SA(1, 0), cA + kstep, voffA); PG8_STAGE(PG8_SB(1, 1), cB + hstepB + kstep, voffB);
;         PG8_WAIT_V(6); PG8_BAR;
;     } else {
;         PG8_STAGE(PG8_SB(0, 0), cB, voffB); PG8_STAGE(PG8_SA(0, 0), cA, voffA); PG8_STAGE(PG8_SB(0, 1), cB + hstepB, voffB); PG8_STAGE(PG8_SA(0, 1), cA + hstepA, voffA);
;         if (wr == 1) PG8_BAR;
;         PG8_WAIT_V(4); PG8_BAR;
.LBB0_657:
	v_mov_b32_e32 v251, 0
	s_cmp_lt_i32 s94, 5
	s_cselect_b64 s[8:9], -1, 0
	s_and_b64 s[0:1], s[8:9], s[0:1]
	s_andn2_b64 vcc, exec, s[0:1]
	s_cbranch_vccnz .LBB0_695
.Lre_p4l0:
	v_readfirstlane_b32 s0, v183
	s_mov_b64 s[10:11], s[90:91]
	s_mov_b64 s[4:5], s[92:93]
	s_lshr_b32 s0, s0, 6
	v_mov_b32_e32 v0, v182
	s_mov_b32 s33, s96
	s_mov_b32 s36, s70
	v_readfirstlane_b32 vcc_lo, v251
	s_cmp_eq_u32 vcc_lo, 0
	s_cbranch_scc1 .Lm0_p4l0
	s_addk_i32 s36, 0x3f8
	s_mov_b32 s33, 0x10000
.Lm0_p4l0:
	v_mov_b32_e32 v12, v183
	s_cmpk_lt_i32 s36, 0x400
	s_movk_i32 s2, 0x400
	v_readfirstlane_b32 s22, v12
	s_cselect_b64 s[6:7], -1, 0
	s_cmpk_gt_i32 s36, 0x3ff
	s_cbranch_scc1 .LBB0_660
	s_ashr_i32 s0, s36, 31
	s_lshr_b32 s0, s0, 29
	s_add_i32 s0, s36, s0
	s_ashr_i32 s1, s0, 3
	s_and_b32 s0, s0, -8
	s_sub_i32 s0, s36, s0
	s_cmp_lt_i32 s0, 0
	s_movk_i32 s3, 0x81
	s_cselect_b32 s3, s3, 0x80
	s_mul_i32 s0, s3, s0
	s_add_i32 s0, s0, s1
	s_ashr_i32 s1, s0, 31
	s_lshr_b32 s1, s1, 27
	s_add_i32 s1, s0, s1
	s_ashr_i32 s3, s1, 5
	s_lshl_b32 s3, s3, 3
	s_sub_i32 s12, 0x100, s3
	s_min_u32 s12, s12, 8
	s_andn2_b32 s1, s1, 31
	s_sub_i32 s13, s0, s1
	v_cvt_f32_ubyte0_e32 v1, s12
	v_cvt_f32_i32_e32 v0, s13
	v_rcp_iflag_f32_e32 v2, v1
	s_ashr_i32 s0, s13, 30
	s_or_b32 s14, s0, 1
	v_mul_f32_e32 v2, v0, v2
	v_trunc_f32_e32 v2, v2
	v_fma_f32 v0, -v2, v1, v0
	v_cvt_i32_f32_e32 v2, v2
	v_cmp_ge_f32_e64 s[0:1], |v0|, v1
	s_and_b64 s[0:1], s[0:1], exec
	s_cselect_b32 s0, s14, 0
	v_readfirstlane_b32 s1, v2
	s_add_i32 s0, s1, s0
	s_sext_i32_i8 s59, s0
	s_mul_i32 s0, s0, s12
	s_sub_i32 s0, s13, s0
	s_sext_i32_i8 s0, s0
	s_add_i32 s0, s3, s0
.LBB0_660:
	s_andn2_b64 vcc, exec, s[6:7]
	s_cbranch_vccnz .LBB0_695
	v_readfirstlane_b32 vcc_lo, v251
	s_cmp_eq_u32 vcc_lo, 0
	s_cbranch_scc1 .Lm1_p4l0
	s_lshr_b32 s0, s70, 2
	s_addk_i32 s0, 0x100
	s_and_b32 s59, s70, 3
.Lm1_p4l0:
	v_ashrrev_i32_e32 v1, 31, v12
	v_lshrrev_b32_e32 v1, 26, v1
	v_add_u32_e32 v1, v12, v1
	v_ashrrev_i32_e32 v13, 6, v1
	v_bfe_i32 v1, v12, 27, 1
	v_lshlrev_b32_e32 v0, 4, v12
	v_lshrrev_b32_e32 v1, 22, v1
	v_add_u32_e32 v1, v0, v1
	v_and_b32_e32 v1, 0xfffffc00, v1
	v_sub_u32_e32 v1, v0, v1
	v_lshrrev_b32_e32 v2, 4, v1
	v_bitop3_b32 v1, v2, v1, 32 bitop3:0x6c
	v_ashrrev_i32_e32 v3, 31, v1
	v_lshrrev_b32_e32 v3, 26, v3
	v_add_u32_e32 v3, v1, v3
	v_ashrrev_i32_e32 v14, 6, v3
	v_and_b32_e32 v3, 0xc0, v3
	v_lshlrev_b32_e32 v2, 3, v13
	v_sub_u32_e32 v1, v1, v3
	v_mov_b32_e32 v3, 1
	v_and_b32_e32 v2, -16, v2
	s_waitcnt lgkmcnt(0)
	v_lshlrev_b32_e32 v4, 5, v13
	v_ashrrev_i16_sdwa v1, v3, sext(v1) dst_sel:DWORD dst_unused:UNUSED_PAD src0_sel:DWORD src1_sel:BYTE_0
	v_add_u32_e32 v2, v14, v2
	v_and_b32_e32 v4, 32, v4
	v_bfe_i32 v15, v1, 0, 16
	v_add_u32_e32 v1, v4, v15
	v_lshlrev_b32_e32 v4, 1, v2
	v_lshrrev_b32_e32 v5, 2, v2
	v_and_b32_e32 v6, 3, v14
	s_mov_b32 s1, 0x7fffffe0
	v_and_b32_e32 v4, 24, v4
	v_and_b32_e32 v5, 4, v5
	v_and_or_b32 v6, v2, s1, v6
	v_or3_b32 v4, v6, v5, v4
	v_lshlrev_b32_e32 v2, 11, v2
	v_lshl_add_u32 v128, v1, 1, v2
	v_mul_lo_u32 v2, v4, s2
	v_add_u32_e32 v0, 0x2000, v0
	v_add_lshl_u32 v130, v2, v1, 1
	v_ashrrev_i32_e32 v1, 31, v0
	v_lshrrev_b32_e32 v1, 22, v1
	v_add_u32_e32 v1, v0, v1
	v_ashrrev_i32_e32 v16, 10, v1
	v_mul_i32_i24_e32 v1, 0x400, v16
	v_sub_u32_e32 v0, v0, v1
	v_lshrrev_b32_e32 v1, 4, v0
	v_bitop3_b32 v0, v1, v0, 32 bitop3:0x6c
	v_ashrrev_i32_e32 v2, 31, v0
	v_lshrrev_b32_e32 v2, 26, v2
	v_add_u32_e32 v2, v0, v2
	v_ashrrev_i32_e32 v17, 6, v2
	v_and_b32_e32 v2, 0xc0, v2
	v_sub_u32_e32 v0, v0, v2
	s_add_u32 s37, s4, 0x14200000
	v_lshlrev_b32_e32 v1, 3, v16
	v_lshlrev_b32_e32 v4, 5, v16
	v_ashrrev_i16_sdwa v0, v3, sext(v0) dst_sel:DWORD dst_unused:UNUSED_PAD src0_sel:DWORD src1_sel:BYTE_0
	s_addc_u32 s38, s5, 0
	v_and_b32_e32 v1, -16, v1
	v_and_b32_e32 v4, 32, v4
	v_bfe_i32 v18, v0, 0, 16
	s_add_u32 s39, s4, 0x690000
	v_add_u32_e32 v1, v17, v1
	v_add_u32_e32 v0, v4, v18
	v_and_b32_e32 v4, 3, v17
	s_addc_u32 s40, s5, 0
	s_ashr_i32 s6, s22, 6
	v_and_or_b32 v4, v1, s1, v4
	s_ashr_i32 s3, s2, 31
	s_ashr_i32 s1, s0, 31
	s_ashr_i32 s41, s22, 8
	s_lshl_b64 s[12:13], s[2:3], 8
	s_lshl_b64 s[14:15], s[2:3], 9
	s_lshl_b32 s42, s6, 10
	s_lshl_b64 s[16:17], s[0:1], 19
	s_add_u32 s30, s37, s16
	s_addc_u32 s31, s38, s17
	s_ashr_i32 s1, s59, 31
	s_mul_i32 s1, s14, s1
	s_mul_hi_u32 s7, s14, s59
	s_lshr_b64 s[16:17], s[2:3], 23
	s_add_i32 s1, s7, s1
	s_mul_i32 s7, s16, s59
	s_add_i32 s1, s1, s7
	s_mul_i32 s7, s14, s59
	v_lshlrev_b32_e32 v2, 1, v1
	v_lshrrev_b32_e32 v3, 2, v1
	s_add_u32 s34, s39, s7
	v_and_b32_e32 v2, 24, v2
	v_and_b32_e32 v3, 4, v3
	s_addc_u32 s35, s40, s1
	s_add_i32 s43, s42, 0
	v_or3_b32 v2, v4, v3, v2
	v_lshlrev_b32_e32 v1, 11, v1
	s_add_i32 m0, s43, 0x10000
	v_lshl_add_u32 v132, v0, 1, v1
	v_mul_lo_u32 v1, v2, s2
	global_load_lds_dwordx4 v130, s[34:35]
	s_add_i32 m0, s43, 0x12000
	v_add_lshl_u32 v134, v1, v0, 1
	s_add_u32 s16, s34, s12
	global_load_lds_dwordx4 v134, s[34:35]
	s_addc_u32 s17, s35, s13
	s_add_i32 m0, s43, 0x14000
	s_add_i32 s44, s43, 0x2000
	global_load_lds_dwordx4 v130, s[16:17]
	s_add_i32 m0, s43, 0x16000
	s_add_u32 s18, s30, 0x40000
	global_load_lds_dwordx4 v134, s[16:17]
	s_mov_b32 m0, s43
	s_addc_u32 s19, s31, 0
	global_load_lds_dwordx4 v128, s[30:31]
	s_mov_b32 m0, s44
	s_add_i32 s45, s43, 0x4000
	global_load_lds_dwordx4 v132, s[30:31]
	s_mov_b32 m0, s45
	s_add_i32 s46, s43, 0x6000
	global_load_lds_dwordx4 v128, s[18:19]
	s_mov_b32 m0, s46
	v_mov_b32_e32 v131, 0
	global_load_lds_dwordx4 v132, s[18:19]
	v_mov_b32_e32 v135, v131
	v_mov_b32_e32 v129, v131
	v_mov_b32_e32 v133, v131
	s_cmp_eq_u32 s41, 1
	s_mov_b32 s47, 0
	v_lshl_add_u64 v[8:9], s[34:35], 0, v[130:131]
	v_lshl_add_u64 v[4:5], s[34:35], 0, v[134:135]
	v_lshl_add_u64 v[2:3], s[16:17], 0, v[130:131]
	v_lshl_add_u64 v[0:1], s[16:17], 0, v[134:135]
	v_lshl_add_u64 v[6:7], s[30:31], 0, v[128:129]
	s_cselect_b64 s[16:17], -1, 0
	s_cmp_lg_u32 s41, 1
	v_lshl_add_u64 v[10:11], s[30:31], 0, v[132:133]
	s_cbranch_scc1 .LBB0_663
	s_barrier
; template <class Epi, class Sched, bool ALIGN_EPI = false, bool SP2 = false>
; __device__ __forceinline__ void gemm_phase(PG8_LAS unsigned char* lds, const Gemm g, const Sched& S, const Epi& E) {
;     ...
;     for (int i = 0; i < 2; ++i) { int R, C; stage_rc(tid * 16 + i * 8192, R, C); const int Rb = Epi::PERM ? ((R & ~31) + perm32(R & 31)) : R;
;         voffA[i] = (unsigned)(R * g.lda + C) * 2u; voffB[i] = (unsigned)(Rb * K + C) * 2u; }
;     const size_t kstep = (size_t)(BK * 2);
;     const size_t hstepA = (size_t)HALF * g.lda * 2, hstepB = (size_t)HALF * K * 2;
;     const size_t tstepA = 2 * hstepA, tstepB = 2 * hstepB;
;     const unsigned ldsw = (unsigned)wid * 1024u;
;     const int aoff = lds_byte(wr * 64 + fr, fq * 8), boff = lds_byte(wc * 32 + fr, fq * 8);
;     ...
;     Unit cur, nxt; int ui = 0;
;     if (!S.next(0, cur)) return;
;     f32x4 acc[2][2][4][2];
; #pragma unroll
;     for (int a = 0; a < 2; ++a)
; #pragma unroll
;         for (int b = 0; b < 2; ++b)
; #pragma unroll
;             for (int m = 0; m < 4; ++m)
; #pragma unroll
;                 for (int n = 0; n < 2; ++n) acc[a][b][m][n] = (f32x4){0.f, 0.f, 0.f, 0.f};
;     bf16x8 At[4][2], B0[2][2], B1[2][2];
;     const char* cA = (cur.pm < g.pm_split) ? (const char*)g.A + (size_t)cur.pm * tstepA : (const char*)g.A2 + (size_t)(cur.pm - g.pm_split) * tstepA; const char* cB = (const char*)g.Bt + (size_t)cur.pn * tstepB;
;     S.a_ready(cur);
;     if constexpr (SP2) {
;         PG8_STAGE(PG8_SB(0, 0), cB, voffB); PG8_STAGE(PG8_SB(0, 1), cB + hstepB, voffB); PG8_STAGE(PG8_SA(0, 0), cA, voffA); PG8_STAGE(PG8_SA(0, 1), cA + hstepA, voffA);
;         if (wr == 1) PG8_BAR;
;         PG8_WAIT_V(2); PG8_BAR;
;         PG8_STAGE(PG8_SB(1, 0), cB + kstep, voffB); PG8_STAGE(PG8_SA(1, 0), cA + kstep, voffA); PG8_STAGE(PG8_SB(1, 1), cB + hstepB + kstep, voffB);
;         PG8_WAIT_V(6); PG8_BAR;
;     } else {
;         PG8_STAGE(PG8_SB(0, 0), cB, voffB); PG8_STAGE(PG8_SA(0, 0), cA, voffA); PG8_STAGE(PG8_SB(0, 1), cB + hstepB, voffB); PG8_STAGE(PG8_SA(0, 1), cA + hstepA, voffA);
;         if (wr == 1) PG8_BAR;
;         PG8_WAIT_V(4); PG8_BAR;
;         PG8_STAGE(PG8_SB(1, 0), cB + kstep, voffB); PG8_STAGE(PG8_SA(1, 0), cA + kstep, voffA); PG8_STAGE(PG8_SB(1, 1), cB + hstepB + kstep, voffB);
;         PG8_WAIT_V(6); PG8_BAR;
;     }
;     for (;;) {
;         const bool has_next = S.next(ui + 1, nxt);
.LBB0_663:
	s_add_u32 s18, s4, 0x3700000
	s_mov_b64 s[20:21], 0x80
	s_addc_u32 s19, s5, 0
	s_add_i32 m0, s43, 0x18000
	v_lshl_add_u64 v[8:9], v[8:9], 0, s[20:21]
	s_waitcnt vmcnt(2)
	s_barrier
	global_load_lds_dwordx4 v[8:9], off
	v_lshl_add_u64 v[4:5], v[4:5], 0, s[20:21]
	s_add_i32 m0, s43, 0x1a000
	s_add_i32 s48, s43, 0x8000
	global_load_lds_dwordx4 v[4:5], off
	v_lshl_add_u64 v[4:5], v[6:7], 0, s[20:21]
	s_mov_b32 m0, s48
	s_add_i32 s49, s43, 0xa000
	global_load_lds_dwordx4 v[4:5], off
	v_lshl_add_u64 v[4:5], v[10:11], 0, s[20:21]
	s_mov_b32 m0, s49
	v_lshl_add_u64 v[2:3], v[2:3], 0, s[20:21]
	global_load_lds_dwordx4 v[4:5], off
	s_add_i32 m0, s43, 0x1c000
	v_lshl_add_u64 v[0:1], v[0:1], 0, s[20:21]
	global_load_lds_dwordx4 v[2:3], off
	s_add_i32 m0, s43, 0x1e000
	v_and_b32_e32 v148, 15, v12
	global_load_lds_dwordx4 v[0:1], off
	s_lshr_b32 s1, s3, 26
	v_bfe_u32 v149, v12, 4, 2
	s_add_i32 s1, s2, s1
	v_lshlrev_b32_e32 v0, 6, v148
	v_lshlrev_b32_e32 v1, 2, v12
	s_and_b32 s50, s6, 3
	s_ashr_i32 s51, s1, 6
	v_lshl_or_b32 v0, v149, 4, v0
	s_lshl_b32 s1, s41, 13
	v_and_b32_e32 v1, 32, v1
	v_bitop3_b32 v2, v0, s1, v1 bitop3:0xde
	s_lshl_b32 s1, s50, 12
	v_bitop3_b32 v150, v0, s1, v1 bitop3:0xde
	v_lshlrev_b32_e32 v0, 14, v16
	v_and_b32_e32 v0, 0xffff8000, v0
	v_lshl_add_u32 v0, v17, 11, v0
	v_and_b32_e32 v1, 1, v16
	v_lshl_or_b32 v0, v1, 6, v0
	v_lshl_add_u32 v136, v18, 1, v0
	v_lshlrev_b32_e32 v0, 14, v13
	s_cmp_gt_i32 s2, 63
	v_and_b32_e32 v0, 0xffff8000, v0
	s_cselect_b64 s[2:3], -1, 0
	s_add_i32 s52, s51, -2
	v_lshl_add_u32 v0, v14, 11, v0
	v_and_b32_e32 v1, 1, v13
	s_waitcnt vmcnt(6)
	s_cmpk_lt_u32 s22, 0x100
	v_lshl_or_b32 v0, v1, 6, v0
	s_cselect_b64 s[22:23], -1, 0
	v_lshl_add_u32 v138, v15, 1, v0
	v_cndmask_b32_e64 v0, 0, 1, s[2:3]
	s_add_i32 s56, 0, 0x10000
	s_add_i32 s57, 0, 0x14000
	v_mbcnt_lo_u32_b32 v1, -1, 0
	s_ashr_i32 s53, s33, 31
	s_ashr_i32 s54, s36, 31
	v_mov_b32_e32 v137, v131
	v_mov_b32_e32 v139, v131
	v_mov_b64_e32 v[140:141], 0x400
	v_mov_b64_e32 v[142:143], 0x3ff
	s_movk_i32 s55, 0x81
	v_add_u32_e32 v151, s56, v150
	v_add_u32_e32 v152, s57, v150
	v_add_u32_e32 v153, 0, v2
	v_mbcnt_hi_u32_b32 v154, -1, v1
	v_cmp_ne_u32_e64 s[2:3], 1, v0
	s_barrier
	s_waitcnt vmcnt(0)
	s_branch .LBB0_666

;     __host__ __device__ bool next(int i, Unit& u) const {
;         const long L = (long)i * G + c; if (L >= nwg) return false;
;         int wgid = (int)L; { const int q = nwg / NXCD, r = nwg % NXCD, xcd = wgid % NXCD, off = wgid / NXCD; wgid = (xcd < r ? xcd * (q + 1) : r * (q + 1) + (xcd - r) * q) + off; }
;         const int nig = WGM * nN, gid = wgid / nig, fm = gid * WGM, gsz = (nM - fm) < WGM ? (nM - fm) : WGM;
;         u.pm = fm + ((wgid % nig) % gsz); u.pn = (wgid % nig) / gsz; return true;
.LBB0_666:
	s_add_i32 s47, s47, 1
	s_mul_i32 s1, s47, s53
	s_mul_hi_u32 s4, s47, s33
	s_add_i32 s1, s4, s1
	s_mul_i32 s4, s47, s33
	s_add_u32 s4, s4, s36
	s_addc_u32 s5, s1, s54
	v_cmp_gt_i64_e32 vcc, s[4:5], v[142:143]
	v_cmp_lt_i64_e64 s[6:7], s[4:5], v[140:141]
	s_cbranch_vccnz .LBB0_668
	s_ashr_i32 s1, s4, 31
	s_lshr_b32 s1, s1, 29
	s_add_i32 s1, s4, s1
	s_ashr_i32 s5, s1, 3
	s_and_b32 s1, s1, -8
	s_sub_i32 s1, s4, s1
	s_cmp_lt_i32 s1, 0
	s_cselect_b32 s4, s55, 0x80
	s_mul_i32 s1, s4, s1
	s_add_i32 s1, s1, s5
	s_ashr_i32 s4, s1, 31
	s_lshr_b32 s4, s4, 27
	s_add_i32 s4, s1, s4
	s_ashr_i32 s5, s4, 5
	s_lshl_b32 s5, s5, 3
	s_sub_i32 s24, 0x100, s5
	s_min_i32 s24, s24, 8
	s_abs_i32 s25, s24
	v_cvt_f32_u32_e32 v0, s25
	s_sub_i32 s27, 0, s25
	s_andn2_b32 s4, s4, 31
	s_sub_i32 s1, s1, s4
	v_rcp_iflag_f32_e32 v0, v0
	s_abs_i32 s4, s1
	s_xor_b32 s26, s1, s24
	s_ashr_i32 s26, s26, 31
	v_mul_f32_e32 v0, 0x4f7ffffe, v0
	v_cvt_u32_f32_e32 v0, v0
	s_nop 0
	v_readfirstlane_b32 s28, v0
	s_mul_i32 s27, s27, s28
	s_mul_hi_u32 s27, s28, s27
	s_add_i32 s28, s28, s27
	s_mul_hi_u32 s27, s4, s28
	s_mul_i32 s28, s27, s25
	s_sub_i32 s4, s4, s28
	s_add_i32 s29, s27, 1
	s_sub_i32 s28, s4, s25
	s_cmp_ge_u32 s4, s25
	s_cselect_b32 s27, s29, s27
	s_cselect_b32 s4, s28, s4
	s_add_i32 s28, s27, 1
	s_cmp_ge_u32 s4, s25
	s_cselect_b32 s4, s28, s27
	s_xor_b32 s4, s4, s26
	s_sub_i32 s58, s4, s26
	s_mul_i32 s4, s58, s24
	s_sub_i32 s1, s1, s4
	s_add_i32 s24, s1, s5

; __device__ __forceinline__ unsigned xb_ld(unsigned* p)              { return __hip_atomic_load(p, __ATOMIC_RELAXED, __HIP_MEMORY_SCOPE_AGENT); }
; __device__ __forceinline__ unsigned xb_add(unsigned* p, unsigned v) { return __hip_atomic_fetch_add(p, v, __ATOMIC_RELAXED, __HIP_MEMORY_SCOPE_AGENT); }
; #define XB_SPIN(cond, bar) do { unsigned _sp = 0; while (cond) { __builtin_amdgcn_s_sleep(1); \
;     if ((++_sp & 255u) == 0u) { if (xb_ld(&(bar)[XB_TMO])) break; if (_sp > XB_SPIN_CAP) { atomicAdd(&(bar)[XB_TMO], 1u); break; } } } } while (0)
; __device__ __forceinline__ void xcd_barrier(const XcdBarrier& b) {
;     asm volatile("s_waitcnt vmcnt(0)" ::: "memory");
;     __syncthreads();
;     if (threadIdx.x == 0) {
;         unsigned* bar = b.bar;
;         __builtin_amdgcn_s_waitcnt(0);
;         unsigned nloc = b.st[0], nx = b.st[1];
;         if (nloc == 0u) { xcd_barrier_complete(bar, b.x, nloc, nx); b.st[0] = nloc; b.st[1] = nx; }
;         const unsigned old = xb_add(&bar[XB_XSUB(b.x)], 1u);
;         const unsigned gen = old / nloc;
;         if (old + 1u == (gen + 1u) * nloc) {
;             __builtin_amdgcn_fence(__ATOMIC_RELEASE, "agent");
;             asm volatile("s_waitcnt vmcnt(0)" ::: "memory");
;             const unsigned og = xb_add(&bar[XB_TOP], 1u);
;             const unsigned tg = og / nx;
;             if (og + 1u == (tg + 1u) * nx) xb_add(&bar[XB_TOPGEN], 1u);
;             else XB_SPIN(xb_ld(&bar[XB_TOPGEN]) == tg, bar);
;             __builtin_amdgcn_fence(__ATOMIC_ACQUIRE, "agent");
;             xb_add(&bar[XB_XGEN(b.x)], 1u);
;             asm volatile("s_waitcnt vmcnt(0)" ::: "memory");
;         } else {
;             XB_SPIN(xb_ld(&bar[XB_XGEN(b.x)]) == gen, bar);
;             __builtin_amdgcn_fence(__ATOMIC_ACQUIRE, "agent");
;             asm volatile("s_waitcnt vmcnt(0)" ::: "memory");
;         }
;     }
;     __syncthreads();
.LBB0_695:
	s_cmp_gt_i32 s95, 5
	s_cselect_b64 s[0:1], -1, 0
	s_and_b64 s[2:3], s[8:9], s[0:1]
	s_andn2_b64 vcc, exec, s[2:3]
	s_cbranch_vccnz .LBB0_740
	v_readfirstlane_b32 vcc_lo, v251
	s_cmp_lg_u32 vcc_lo, 0
	s_cbranch_scc1 .LBB0_740
	s_waitcnt vmcnt(0)
	s_waitcnt vmcnt(0) lgkmcnt(0)
	s_barrier
	s_mov_b64 s[2:3], exec
	v_readlane_b32 s4, v250, 0
	v_readlane_b32 s5, v250, 1
	s_and_b64 s[4:5], s[2:3], s[4:5]
	s_mov_b64 exec, s[4:5]
	s_cbranch_execz .LBB0_739
	s_add_i32 s4, 0, 0x23fc0
	v_mov_b32_e32 v0, s4
	s_waitcnt vmcnt(0) expcnt(0) lgkmcnt(0)
	ds_read_b32 v2, v0
	s_add_i32 s4, 0, 0x23fc4
	v_mov_b32_e32 v0, s4
	ds_read_b32 v0, v0
	s_waitcnt lgkmcnt(1)
	v_cmp_ne_u32_e32 vcc, 0, v2
	s_cbranch_vccnz .LBB0_710
	s_add_u32 s4, s72, 0x1000
	s_addc_u32 s5, s73, 0
	s_add_u32 s6, s72, 0x1100
	s_addc_u32 s7, s73, 0
	s_add_u32 s8, s72, 0x1200
	s_addc_u32 s9, s73, 0
	s_mul_i32 s18, s97, s71
	s_add_u32 s10, s72, 0x1300
	s_mul_i32 s18, s18, s96
	s_addc_u32 s11, s73, 0
	s_mov_b32 s19, 1
	v_mov_b32_e32 v16, 0
	s_branch .LBB0_700

; __device__ __forceinline__ unsigned pk2(float lo, float hi) { return f2bf(lo) | (f2bf(hi) << 16); }
; __device__ __forceinline__ void nr_pass(bf16* X, const bf16* Y, const float* SSQ, float* ssqX, const float* g, float* out  , int gw, int NGW, int lane) {
;     f32x4 gv[4];
; #pragma unroll
;     for (int j = 0; j < 4; ++j) gv[j] = *((const f32x4*)g + lane + 64 * j);
;     for (int r = gw; r < M_REAL; r += NGW) {
;         const float part = SSQ[(size_t)r * 32 + (lane & 31)];
;         const float s = rsqrtf(half_sum32(part) * (1.0f / 1024.0f) + EPS);
;         v2u* x8 = (v2u*)(X + (size_t)r * 1024) + lane; const v2u* y8 = (const v2u*)(Y + (size_t)r * 1024) + lane;
;         f32x4 v[4]; float s2 = 0.f;
; #pragma unroll
;         for (int j = 0; j < 4; ++j) { const v2u xv = x8[64 * j], yv = __builtin_nontemporal_load(&y8[64 * j]);
;             v[j].x = bflo(xv.x) + bflo(yv.x) * s * gv[j].x; v[j].y = bfhi(xv.x) + bfhi(yv.x) * s * gv[j].y;
;             v[j].z = bflo(xv.y) + bflo(yv.y) * s * gv[j].z; v[j].w = bfhi(xv.y) + bfhi(yv.y) * s * gv[j].w;
;             s2 += (v[j].x * v[j].x + v[j].y * v[j].y) + (v[j].z * v[j].z + v[j].w * v[j].w); }
;         if (out == nullptr) {
;             s2 = wave_sum(s2);
; #pragma unroll
;             for (int j = 0; j < 4; ++j) x8[64 * j] = (v2u){pk2(v[j].x, v[j].y), pk2(v[j].z, v[j].w)};
;             if (lane == 0) ssqX[r] = s2;
.LBB0_740:
	v_readfirstlane_b32 vcc_lo, v251
	v_mov_b32_e32 v251, 1
	s_cmp_eq_u32 vcc_lo, 0
	s_cbranch_scc1 .Lre_p4l0
	s_cmp_lt_i32 s94, 6
	s_cselect_b64 s[4:5], -1, 0
	s_and_b64 s[0:1], s[4:5], s[0:1]
	s_andn2_b64 vcc, exec, s[0:1]
	s_cbranch_vccnz .LBB0_746
	v_readfirstlane_b32 s0, v183
	s_mov_b64 s[2:3], s[90:91]
	s_mov_b64 s[14:15], s[92:93]
	s_lshr_b32 s0, s0, 6
	s_waitcnt lgkmcnt(0)
	v_mov_b32_e32 v20, v182
	s_mov_b32 s6, s96
	s_mov_b32 s1, s70
	s_lshl_b32 s1, s1, 3
	s_mov_b32 s63, 0x10120
	s_cmp_lt_u32 s70, 8
	s_cbranch_scc1 .Lnr_tail_p4l0
	s_sub_i32 s1, s1, 64
	s_sub_i32 s6, s6, 8
	s_mov_b32 s63, 0x10000
	s_branch .Lnr_go_p4l0
.Lnr_tail_p4l0:
	s_waitcnt vmcnt(0) lgkmcnt(0)
	s_barrier
	s_cmp_lg_u32 s0, 0
	s_cbranch_scc1 .Lnr_tsd_p4l0
	s_mov_b64 exec, 1
	buffer_wbl2 sc1
	s_waitcnt vmcnt(0)
	v_mov_b32_e32 v252, 0
	v_mov_b32_e32 v253, 1
	global_atomic_add v252, v253, s[92:93] offset:2048
	s_waitcnt vmcnt(0)
.Lnr_tspin_p4l0:
	global_load_dword v254, v252, s[92:93] offset:2048 sc1
	s_waitcnt vmcnt(0)
	v_readfirstlane_b32 vcc_lo, v254
	s_cmp_ge_u32 vcc_lo, 8
	s_cbranch_scc1 .Lnr_tspun_p4l0
	s_sleep 2
	s_branch .Lnr_tspin_p4l0
.Lnr_tspun_p4l0:
	buffer_inv sc1
	s_waitcnt vmcnt(0)
	s_mov_b64 exec, -1
.Lnr_tsd_p4l0:
	s_barrier
	s_add_i32 s1, s1, 0x10000
	s_mov_b32 s6, 8
.Lnr_go_p4l0:
	s_add_i32 s18, s1, s0
	s_cmp_ge_i32 s18, s63
	s_cbranch_scc1 .LBB0_746
	v_readlane_b32 s36, v250, 2
	v_ashrrev_i32_e32 v21, 31, v20
	v_readlane_b32 s42, v250, 8
	v_readlane_b32 s43, v250, 9
	v_mbcnt_lo_u32_b32 v18, -1, 0
	v_mbcnt_hi_u32_b32 v18, -1, v18
	v_lshl_add_u64 v[16:17], v[20:21], 4, s[42:43]
	global_load_dwordx4 v[0:3], v[16:17], off
	global_load_dwordx4 v[4:7], v[16:17], off offset:1024
	global_load_dwordx4 v[8:11], v[16:17], off offset:2048
	global_load_dwordx4 v[12:15], v[16:17], off offset:3072
	v_and_b32_e32 v19, 64, v18
	s_lshl_b32 s6, s6, 3
	s_ashr_i32 s7, s0, 31
	s_ashr_i32 s8, s1, 31
	v_xor_b32_e32 v22, 1, v18
	v_add_u32_e32 v19, 64, v19
	s_add_u32 s22, s0, s1
	v_xor_b32_e32 v23, 2, v18
	v_cmp_lt_i32_e64 s[0:1], v22, v19
	v_xor_b32_e32 v25, 4, v18
	v_xor_b32_e32 v26, 8, v18
	v_cndmask_b32_e64 v22, v18, v22, s[0:1]
	v_cmp_lt_i32_e64 s[0:1], v23, v19
	v_xor_b32_e32 v27, 16, v18
	v_xor_b32_e32 v28, 32, v18
	v_cndmask_b32_e64 v23, v18, v23, s[0:1]
	v_cmp_lt_i32_e64 s[0:1], v25, v19
	s_addc_u32 s23, s7, s8
	s_lshl_b64 s[8:9], s[22:23], 2
	v_cndmask_b32_e64 v29, v18, v25, s[0:1]
	v_cmp_lt_i32_e64 s[0:1], v26, v19
	v_and_b32_e32 v16, 31, v20
	v_mov_b32_e32 v17, 0
	v_cndmask_b32_e64 v30, v18, v26, s[0:1]
	v_cmp_lt_i32_e64 s[0:1], v27, v19
	v_lshlrev_b32_e32 v16, 2, v16
	s_mov_b64 s[16:17], 0x3700000
	v_cndmask_b32_e64 v31, v18, v27, s[0:1]
	v_cmp_lt_i32_e64 s[0:1], v28, v19
	v_cmp_eq_u32_e32 vcc, 0, v20
	v_mov_b32_e32 v24, 0x358637bd
	v_cndmask_b32_e64 v18, v18, v28, s[0:1]
	s_add_u32 s0, s14, s8
	s_addc_u32 s1, s15, s9
	s_add_u32 s8, s0, 0x3f80000
	s_addc_u32 s9, s1, 0
	s_ashr_i32 s7, s6, 31
	s_lshl_b64 s[0:1], s[22:23], 7
	s_lshl_b64 s[10:11], s[6:7], 2
	s_add_u32 s0, s14, s0
	s_addc_u32 s1, s15, s1
	s_lshl_b64 s[12:13], s[6:7], 7
	s_add_u32 s14, s14, 0x4000400
	v_lshlrev_b32_e32 v28, 2, v30
	v_lshlrev_b32_e32 v30, 2, v18
	v_lshl_add_u64 v[18:19], s[0:1], 0, v[16:17]
	s_addc_u32 s15, s15, 0
	s_lshl_b64 s[0:1], s[22:23], 11
	s_mov_b32 s19, 0x800000
	s_movk_i32 s20, 0x7fff
	v_lshlrev_b32_e32 v25, 2, v22
	v_lshlrev_b32_e32 v26, 2, v23
	v_lshlrev_b32_e32 v27, 2, v29
	v_lshlrev_b32_e32 v29, 2, v31
	v_lshl_add_u64 v[18:19], v[18:19], 0, s[16:17]
	s_lshl_b64 s[16:17], s[6:7], 11
	v_lshl_add_u64 v[20:21], v[20:21], 3, s[0:1]
	v_mov_b32_e32 v16, 1
	v_readlane_b32 s37, v250, 3
	v_readlane_b32 s38, v250, 4
	v_readlane_b32 s39, v250, 5
	v_readlane_b32 s40, v250, 6
	v_readlane_b32 s41, v250, 7
	v_readlane_b32 s44, v250, 10
	v_readlane_b32 s45, v250, 11
	v_readlane_b32 s46, v250, 12
	v_readlane_b32 s47, v250, 13
	v_readlane_b32 s48, v250, 14
	v_readlane_b32 s49, v250, 15
	v_readlane_b32 s50, v250, 16
	v_readlane_b32 s51, v250, 17
	s_waitcnt vmcnt(0)
	v_mov_b32_e32 v22, v1
	v_mov_b32_e32 v23, v3
	v_mov_b32_e32 v1, v2
	v_mov_b32_e32 v2, v5
	v_mov_b32_e32 v3, v7
	v_mov_b32_e32 v5, v6
	v_mov_b32_e32 v6, v9
	v_mov_b32_e32 v7, v11
	v_mov_b32_e32 v9, v10
	v_mov_b32_e32 v10, v13
	v_mov_b32_e32 v11, v15
	v_mov_b32_e32 v13, v14
	s_branch .LBB0_744
.LBB0_743:
	s_or_b64 exec, exec, s[0:1]
	s_add_i32 s18, s18, s6
	s_add_u32 s8, s8, s10
	s_addc_u32 s9, s9, s11
	v_lshl_add_u64 v[18:19], v[18:19], 0, s[12:13]
	s_cmp_lt_i32 s18, s63
	v_lshl_add_u64 v[20:21], v[20:21], 0, s[16:17]
	s_cbranch_scc0 .LBB0_746

; template <class Epi, class Sched, bool ALIGN_EPI = false, bool SP2 = false>
; __device__ __forceinline__ void gemm_phase(PG8_LAS unsigned char* lds, const Gemm g, const Sched& S, const Epi& E) {
;     ...
;     const int wid = __builtin_amdgcn_readfirstlane(tid >> 6), lane = tid & 63, wr = wid >> 2, wc = wid & 3, fr = lane & 15, fq = lane >> 4;
;     int K = g.K; asm volatile("" : "+s"(K));
;     const int nt = K / BK;
;     unsigned voffA[2], voffB[2];
; #pragma unroll
;     for (int i = 0; i < 2; ++i) { int R, C; stage_rc(tid * 16 + i * 8192, R, C); const int Rb = Epi::PERM ? ((R & ~31) + perm32(R & 31)) : R;
;         voffA[i] = (unsigned)(R * g.lda + C) * 2u; voffB[i] = (unsigned)(Rb * K + C) * 2u; }
;     const size_t kstep = (size_t)(BK * 2);
;     const size_t hstepA = (size_t)HALF * g.lda * 2, hstepB = (size_t)HALF * K * 2;
;     const size_t tstepA = 2 * hstepA, tstepB = 2 * hstepB;
;     const unsigned ldsw = (unsigned)wid * 1024u;
;     const int aoff = lds_byte(wr * 64 + fr, fq * 8), boff = lds_byte(wc * 32 + fr, fq * 8);
;     ...
;     Unit cur, nxt; int ui = 0;
;     if (!S.next(0, cur)) return;
;     f32x4 acc[2][2][4][2];
; #pragma unroll
;     for (int a = 0; a < 2; ++a)
; #pragma unroll
;         for (int b = 0; b < 2; ++b)
; #pragma unroll
;             for (int m = 0; m < 4; ++m)
; #pragma unroll
;                 for (int n = 0; n < 2; ++n) acc[a][b][m][n] = (f32x4){0.f, 0.f, 0.f, 0.f};
;     bf16x8 At[4][2], B0[2][2], B1[2][2];
;     const char* cA = (cur.pm < g.pm_split) ? (const char*)g.A + (size_t)cur.pm * tstepA : (const char*)g.A2 + (size_t)(cur.pm - g.pm_split) * tstepA; const char* cB = (const char*)g.Bt + (size_t)cur.pn * tstepB;
;     S.a_ready(cur);
;     if constexpr (SP2) {
;         PG8_STAGE(PG8_SB(0, 0), cB, voffB); PG8_STAGE(PG8_SB(0, 1), cB + hstepB, voffB); PG8_STAGE(PG8_SA(0, 0), cA, voffA); PG8_STAGE(PG8_SA(0, 1), cA + hstepA, voffA);
;         if (wr == 1) PG8_BAR;
;         PG8_WAIT_V(2); PG8_BAR;
;         PG8_STAGE(PG8_SB(1, 0), cB + kstep, voffB); PG8_STAGE(PG8_SA(1, 0), cA + kstep, voffA); PG8_STAGE(PG8_SB(1, 1), cB + hstepB + kstep, voffB);
;         PG8_WAIT_V(6); PG8_BAR;
;     } else {
;         PG8_STAGE(PG8_SB(0, 0), cB, voffB); PG8_STAGE(PG8_SA(0, 0), cA, voffA); PG8_STAGE(PG8_SB(0, 1), cB + hstepB, voffB); PG8_STAGE(PG8_SA(0, 1), cA + hstepA, voffA);
;         if (wr == 1) PG8_BAR;
;         PG8_WAIT_V(4); PG8_BAR;
.LBB0_864:
	v_mov_b32_e32 v251, 0
	s_cmp_lt_i32 s94, 8
	s_cselect_b64 s[4:5], -1, 0
	s_and_b64 s[0:1], s[4:5], s[2:3]
	s_andn2_b64 vcc, exec, s[0:1]
	s_cbranch_vccnz .LBB0_907
.Lre_p7l0:
	v_readfirstlane_b32 s0, v183
	s_mov_b64 s[2:3], s[92:93]
	s_mov_b64 s[6:7], s[90:91]
	s_lshr_b32 s0, s0, 6
	v_mov_b32_e32 v0, v182
	s_mov_b32 s33, s70
	s_mov_b32 s36, s96
	v_readfirstlane_b32 vcc_lo, v251
	s_cmp_eq_u32 vcc_lo, 0
	s_cbranch_scc1 .Lm0_p7l0
	s_addk_i32 s33, 0x3f8
	s_mov_b32 s36, 0x10000
.Lm0_p7l0:
	v_mov_b32_e32 v12, v183
	s_cmpk_lt_i32 s33, 0x400
	s_movk_i32 s0, 0xb00
	v_readfirstlane_b32 s22, v12
	s_cselect_b64 s[8:9], -1, 0
	s_cmpk_gt_i32 s33, 0x3ff
	s_cbranch_scc1 .LBB0_867
	s_ashr_i32 s1, s33, 31
	s_lshr_b32 s1, s1, 29
	s_add_i32 s1, s33, s1
	s_ashr_i32 s10, s1, 3
	s_and_b32 s1, s1, -8
	s_sub_i32 s1, s33, s1
	s_cmp_lt_i32 s1, 0
	s_movk_i32 s11, 0x81
	s_cselect_b32 s11, s11, 0x80
	s_mul_i32 s1, s11, s1
	s_add_i32 s1, s1, s10
	s_ashr_i32 s10, s1, 31
	s_lshr_b32 s10, s10, 27
	s_add_i32 s10, s1, s10
	s_ashr_i32 s11, s10, 5
	s_lshl_b32 s12, s11, 3
	s_sub_i32 s11, 0x100, s12
	s_min_u32 s13, s11, 8
	s_andn2_b32 s10, s10, 31
	s_sub_i32 s1, s1, s10
	v_cvt_f32_ubyte0_e32 v1, s13
	v_cvt_f32_i32_e32 v0, s1
	v_rcp_iflag_f32_e32 v2, v1
	s_ashr_i32 s10, s1, 30
	s_or_b32 s14, s10, 1
	v_mul_f32_e32 v2, v0, v2
	v_trunc_f32_e32 v2, v2
	v_fma_f32 v0, -v2, v1, v0
	v_cvt_i32_f32_e32 v2, v2
	v_cmp_ge_f32_e64 s[10:11], |v0|, v1
	s_and_b64 s[10:11], s[10:11], exec
	s_cselect_b32 s10, s14, 0
	v_readfirstlane_b32 s11, v2
	s_add_i32 s10, s11, s10
	s_sext_i32_i8 s60, s10
	s_mul_i32 s10, s10, s13
	s_sub_i32 s1, s1, s10
	s_sext_i32_i8 s1, s1
	s_add_i32 s34, s12, s1
.LBB0_867:
	s_andn2_b64 vcc, exec, s[8:9]
	s_cbranch_vccnz .LBB0_907
	v_readfirstlane_b32 vcc_lo, v251
	s_cmp_eq_u32 vcc_lo, 0
	s_cbranch_scc1 .Lm1_p7l0
	s_lshr_b32 s34, s70, 2
	s_addk_i32 s34, 0x100
	s_and_b32 s60, s70, 3
.Lm1_p7l0:
	v_ashrrev_i32_e32 v1, 31, v12
	v_lshrrev_b32_e32 v1, 26, v1
	v_add_u32_e32 v1, v12, v1
	v_ashrrev_i32_e32 v13, 6, v1
	v_bfe_i32 v1, v12, 27, 1
	v_lshlrev_b32_e32 v0, 4, v12
	v_lshrrev_b32_e32 v1, 22, v1
	v_add_u32_e32 v1, v0, v1
	v_and_b32_e32 v1, 0xfffffc00, v1
	v_sub_u32_e32 v1, v0, v1
	v_lshrrev_b32_e32 v2, 4, v1
	v_bitop3_b32 v1, v2, v1, 32 bitop3:0x6c
	v_ashrrev_i32_e32 v3, 31, v1
	v_lshrrev_b32_e32 v3, 26, v3
	v_lshlrev_b32_e32 v2, 3, v13
	v_add_u32_e32 v3, v1, v3
	v_and_b32_e32 v2, -16, v2
	v_ashrrev_i32_e32 v14, 6, v3
	v_and_b32_e32 v3, 0xc0, v3
	v_add_u32_e32 v2, v14, v2
	s_waitcnt lgkmcnt(0)
	v_lshlrev_b32_e32 v4, 5, v13
	v_sub_u32_e32 v1, v1, v3
	v_mov_b32_e32 v3, 1
	v_and_b32_e32 v15, 32, v4
	v_ashrrev_i16_sdwa v1, v3, sext(v1) dst_sel:DWORD dst_unused:UNUSED_PAD src0_sel:DWORD src1_sel:BYTE_0
	v_lshlrev_b32_e32 v4, 1, v2
	v_lshrrev_b32_e32 v5, 2, v2
	v_and_b32_e32 v6, 3, v14
	s_mov_b32 s1, 0x7fffffe0
	v_bfe_i32 v16, v1, 0, 16
	v_and_b32_e32 v4, 24, v4
	v_and_b32_e32 v5, 4, v5
	v_and_or_b32 v6, v2, s1, v6
	s_movk_i32 s24, 0xb00
	v_add_u32_e32 v1, v15, v16
	v_or3_b32 v4, v6, v5, v4
	v_mul_lo_u32 v2, v2, s24
	v_add_lshl_u32 v128, v1, v2, 1
	v_mul_lo_u32 v2, v4, s0
	v_add_u32_e32 v0, 0x2000, v0
	v_add_lshl_u32 v130, v2, v1, 1
	v_ashrrev_i32_e32 v1, 31, v0
	v_lshrrev_b32_e32 v1, 22, v1
	v_add_u32_e32 v1, v0, v1
	v_ashrrev_i32_e32 v17, 10, v1
	v_mul_i32_i24_e32 v1, 0x400, v17
	v_sub_u32_e32 v0, v0, v1
	v_lshrrev_b32_e32 v1, 4, v0
	v_bitop3_b32 v0, v1, v0, 32 bitop3:0x6c
	v_ashrrev_i32_e32 v2, 31, v0
	v_lshrrev_b32_e32 v2, 26, v2
	s_add_u32 s37, s2, 0x14200000
	v_lshlrev_b32_e32 v1, 3, v17
	v_add_u32_e32 v2, v0, v2
	s_addc_u32 s38, s3, 0
	v_and_b32_e32 v1, -16, v1
	v_ashrrev_i32_e32 v19, 6, v2
	v_lshlrev_b32_e32 v4, 5, v17
	s_add_u32 s39, s2, 0x1390000
	v_add_u32_e32 v1, v19, v1
	v_and_b32_e32 v18, 32, v4
	v_and_b32_e32 v4, 3, v19
	s_addc_u32 s40, s3, 0
	s_ashr_i32 s20, s22, 6
	v_and_or_b32 v4, v1, s1, v4
	s_ashr_i32 s1, s0, 31
	s_ashr_i32 s41, s22, 8
	s_lshl_b64 s[8:9], s[0:1], 8
	s_lshl_b64 s[10:11], s[0:1], 9
	s_lshl_b32 s42, s20, 10
	s_add_i32 s12, s34, 0xffffff76
	s_ashr_i32 s13, s34, 31
	s_cmpk_lt_i32 s34, 0x8a
	s_cselect_b32 s12, s34, s12
	s_cselect_b32 s13, s13, 0
	s_mul_i32 s13, s13, 0x160000
	s_mul_hi_u32 s16, s12, 0x160000
	s_cselect_b32 s14, s38, s7
	s_cselect_b32 s15, s37, s6
	s_add_i32 s16, s16, s13
	s_mul_i32 s12, s12, 0x160000
	s_add_u32 s28, s15, s12
	s_addc_u32 s29, s14, s16
	s_ashr_i32 s12, s60, 31
	s_mul_i32 s12, s10, s12
	s_mul_hi_u32 s13, s10, s60
	s_add_i32 s14, s13, s12
	s_lshr_b64 s[12:13], s[0:1], 23
	v_and_b32_e32 v2, 0xc0, v2
	s_mul_i32 s12, s12, s60
	v_sub_u32_e32 v0, v0, v2
	s_add_i32 s14, s14, s12
	s_mul_i32 s12, s10, s60
	v_ashrrev_i16_sdwa v0, v3, sext(v0) dst_sel:DWORD dst_unused:UNUSED_PAD src0_sel:DWORD src1_sel:BYTE_0
	v_lshlrev_b32_e32 v2, 1, v1
	v_lshrrev_b32_e32 v3, 2, v1
	s_add_u32 s30, s39, s12
	v_bfe_i32 v20, v0, 0, 16
	v_and_b32_e32 v2, 24, v2
	v_and_b32_e32 v3, 4, v3
	s_addc_u32 s31, s40, s14
	s_add_i32 s43, s42, 0
	v_add_u32_e32 v0, v18, v20
	v_or3_b32 v2, v4, v3, v2
	v_mul_lo_u32 v1, v1, s24
	s_add_i32 m0, s43, 0x10000
	v_add_lshl_u32 v132, v0, v1, 1
	v_mul_lo_u32 v1, v2, s0
	global_load_lds_dwordx4 v130, s[30:31]
	s_add_i32 m0, s43, 0x12000
	v_add_lshl_u32 v134, v1, v0, 1
	s_add_u32 s12, s30, s8
	global_load_lds_dwordx4 v134, s[30:31]
	s_addc_u32 s13, s31, s9
	s_add_i32 m0, s43, 0x14000
	s_add_i32 s44, s43, 0x2000
	global_load_lds_dwordx4 v130, s[12:13]
	s_add_i32 m0, s43, 0x16000
	s_add_u32 s14, s28, 0xb0000
	global_load_lds_dwordx4 v134, s[12:13]
	s_mov_b32 m0, s43
	s_addc_u32 s15, s29, 0
	global_load_lds_dwordx4 v128, s[28:29]
	s_mov_b32 m0, s44
	s_add_i32 s45, s43, 0x4000
	global_load_lds_dwordx4 v132, s[28:29]
	s_mov_b32 m0, s45
	s_add_i32 s46, s43, 0x6000
	global_load_lds_dwordx4 v128, s[14:15]
	s_mov_b32 m0, s46
	v_mov_b32_e32 v131, 0
	global_load_lds_dwordx4 v132, s[14:15]
	v_mov_b32_e32 v135, v131
	v_mov_b32_e32 v129, v131
	v_mov_b32_e32 v133, v131
	s_cmp_eq_u32 s41, 1
	s_mov_b32 s47, 0
	v_lshl_add_u64 v[8:9], s[30:31], 0, v[130:131]
	v_lshl_add_u64 v[4:5], s[30:31], 0, v[134:135]
	v_lshl_add_u64 v[2:3], s[12:13], 0, v[130:131]
	v_lshl_add_u64 v[0:1], s[12:13], 0, v[134:135]
	v_lshl_add_u64 v[6:7], s[28:29], 0, v[128:129]
	s_cselect_b64 s[12:13], -1, 0
	s_cmp_lg_u32 s41, 1
	v_lshl_add_u64 v[10:11], s[28:29], 0, v[132:133]
	s_cbranch_scc1 .LBB0_870
	s_barrier
; template <class Epi, class Sched, bool ALIGN_EPI = false, bool SP2 = false>
; __device__ __forceinline__ void gemm_phase(PG8_LAS unsigned char* lds, const Gemm g, const Sched& S, const Epi& E) {
;     ...
;     for (int i = 0; i < 2; ++i) { int R, C; stage_rc(tid * 16 + i * 8192, R, C); const int Rb = Epi::PERM ? ((R & ~31) + perm32(R & 31)) : R;
;         voffA[i] = (unsigned)(R * g.lda + C) * 2u; voffB[i] = (unsigned)(Rb * K + C) * 2u; }
;     const size_t kstep = (size_t)(BK * 2);
;     const size_t hstepA = (size_t)HALF * g.lda * 2, hstepB = (size_t)HALF * K * 2;
;     const size_t tstepA = 2 * hstepA, tstepB = 2 * hstepB;
;     const unsigned ldsw = (unsigned)wid * 1024u;
;     const int aoff = lds_byte(wr * 64 + fr, fq * 8), boff = lds_byte(wc * 32 + fr, fq * 8);
;     ...
;     Unit cur, nxt; int ui = 0;
;     if (!S.next(0, cur)) return;
;     f32x4 acc[2][2][4][2];
; #pragma unroll
;     for (int a = 0; a < 2; ++a)
; #pragma unroll
;         for (int b = 0; b < 2; ++b)
; #pragma unroll
;             for (int m = 0; m < 4; ++m)
; #pragma unroll
;                 for (int n = 0; n < 2; ++n) acc[a][b][m][n] = (f32x4){0.f, 0.f, 0.f, 0.f};
;     bf16x8 At[4][2], B0[2][2], B1[2][2];
;     const char* cA = (cur.pm < g.pm_split) ? (const char*)g.A + (size_t)cur.pm * tstepA : (const char*)g.A2 + (size_t)(cur.pm - g.pm_split) * tstepA; const char* cB = (const char*)g.Bt + (size_t)cur.pn * tstepB;
;     S.a_ready(cur);
;     if constexpr (SP2) {
;         PG8_STAGE(PG8_SB(0, 0), cB, voffB); PG8_STAGE(PG8_SB(0, 1), cB + hstepB, voffB); PG8_STAGE(PG8_SA(0, 0), cA, voffA); PG8_STAGE(PG8_SA(0, 1), cA + hstepA, voffA);
;         if (wr == 1) PG8_BAR;
;         PG8_WAIT_V(2); PG8_BAR;
;         PG8_STAGE(PG8_SB(1, 0), cB + kstep, voffB); PG8_STAGE(PG8_SA(1, 0), cA + kstep, voffA); PG8_STAGE(PG8_SB(1, 1), cB + hstepB + kstep, voffB);
;         PG8_WAIT_V(6); PG8_BAR;
;     } else {
;         PG8_STAGE(PG8_SB(0, 0), cB, voffB); PG8_STAGE(PG8_SA(0, 0), cA, voffA); PG8_STAGE(PG8_SB(0, 1), cB + hstepB, voffB); PG8_STAGE(PG8_SA(0, 1), cA + hstepA, voffA);
;         if (wr == 1) PG8_BAR;
;         PG8_WAIT_V(4); PG8_BAR;
;         PG8_STAGE(PG8_SB(1, 0), cB + kstep, voffB); PG8_STAGE(PG8_SA(1, 0), cA + kstep, voffA); PG8_STAGE(PG8_SB(1, 1), cB + hstepB + kstep, voffB);
;         PG8_WAIT_V(6); PG8_BAR;
;     }
;     for (;;) {
;         const bool has_next = S.next(ui + 1, nxt);
.LBB0_870:
	s_add_u32 s14, s2, 0xc100000
	s_addc_u32 s15, s3, 0
	s_add_u32 s16, s2, 0x3700000
	s_mov_b64 s[18:19], 0x80
	s_addc_u32 s17, s3, 0
	s_add_i32 m0, s43, 0x18000
	v_lshl_add_u64 v[8:9], v[8:9], 0, s[18:19]
	s_waitcnt vmcnt(2)
	s_barrier
	global_load_lds_dwordx4 v[8:9], off
	v_lshl_add_u64 v[4:5], v[4:5], 0, s[18:19]
	s_add_i32 m0, s43, 0x1a000
	s_add_i32 s48, s43, 0x8000
	global_load_lds_dwordx4 v[4:5], off
	v_lshl_add_u64 v[4:5], v[6:7], 0, s[18:19]
	s_mov_b32 m0, s48
	s_add_i32 s49, s43, 0xa000
	global_load_lds_dwordx4 v[4:5], off
	v_lshl_add_u64 v[4:5], v[10:11], 0, s[18:19]
	s_mov_b32 m0, s49
	v_lshl_add_u64 v[2:3], v[2:3], 0, s[18:19]
	global_load_lds_dwordx4 v[4:5], off
	s_add_i32 m0, s43, 0x1c000
	v_lshl_add_u64 v[0:1], v[0:1], 0, s[18:19]
	global_load_lds_dwordx4 v[2:3], off
	s_add_i32 m0, s43, 0x1e000
	v_and_b32_e32 v148, 15, v12
	global_load_lds_dwordx4 v[0:1], off
	s_lshr_b32 s1, s1, 26
	v_bfe_u32 v149, v12, 4, 2
	s_add_i32 s1, s0, s1
	v_lshlrev_b32_e32 v0, 6, v148
	v_lshlrev_b32_e32 v1, 2, v12
	s_and_b32 s50, s20, 3
	s_ashr_i32 s51, s1, 6
	v_lshl_or_b32 v0, v149, 4, v0
	s_lshl_b32 s1, s41, 13
	v_and_b32_e32 v1, 32, v1
	v_bitop3_b32 v2, v0, s1, v1 bitop3:0xde
	s_lshl_b32 s1, s50, 12
	v_bitop3_b32 v150, v0, s1, v1 bitop3:0xde
	v_lshrrev_b32_e32 v1, 1, v17
	v_mul_lo_u32 v0, v19, s24
	s_mov_b32 s2, 0xb000
	s_cmp_gt_i32 s0, 63
	v_mad_u64_u32 v[0:1], s[0:1], v1, s2, v[0:1]
	v_or_b32_e32 v0, v0, v18
	v_add_lshl_u32 v0, v0, v20, 1
	v_mov_b32_e32 v1, v131
	s_mov_b64 s[0:1], 0xb0080
	v_lshl_add_u64 v[136:137], v[0:1], 0, s[0:1]
	v_lshrrev_b32_e32 v1, 1, v13
	v_mul_lo_u32 v0, v14, s24
	v_mad_u64_u32 v[0:1], s[2:3], v1, s2, v[0:1]
	s_cselect_b64 s[20:21], -1, 0
	s_add_i32 s52, s51, -2
	v_or_b32_e32 v0, v0, v15
	s_waitcnt vmcnt(6)
	s_cmpk_lt_u32 s22, 0x100
	v_add_lshl_u32 v0, v0, v16, 1
	v_mov_b32_e32 v1, v131
	s_cselect_b64 s[22:23], -1, 0
	v_lshl_add_u64 v[138:139], v[0:1], 0, s[0:1]
	s_add_i32 s56, 0, 0x10000
	s_add_i32 s57, 0, 0x14000
	v_mbcnt_lo_u32_b32 v0, -1, 0
	s_ashr_i32 s53, s36, 31
	s_ashr_i32 s54, s33, 31
	v_mov_b64_e32 v[140:141], 0x400
	v_mov_b64_e32 v[142:143], 0x3ff
	s_movk_i32 s55, 0x81
	v_add_u32_e32 v151, s56, v150
	v_add_u32_e32 v152, s57, v150
	v_add_u32_e32 v153, 0, v2
	v_mbcnt_hi_u32_b32 v154, -1, v0
	s_barrier
	s_waitcnt vmcnt(0)
	s_branch .LBB0_873

;     __host__ __device__ bool next(int i, Unit& u) const {
;         const long L = (long)i * G + c; if (L >= nwg) return false;
;         int wgid = (int)L; { const int q = nwg / NXCD, r = nwg % NXCD, xcd = wgid % NXCD, off = wgid / NXCD; wgid = (xcd < r ? xcd * (q + 1) : r * (q + 1) + (xcd - r) * q) + off; }
;         const int nig = WGM * nN, gid = wgid / nig, fm = gid * WGM, gsz = (nM - fm) < WGM ? (nM - fm) : WGM;
;         u.pm = fm + ((wgid % nig) % gsz); u.pn = (wgid % nig) / gsz; return true;
.LBB0_873:
	s_add_i32 s47, s47, 1
	s_mul_i32 s0, s47, s53
	s_mul_hi_u32 s1, s47, s36
	s_add_i32 s1, s1, s0
	s_mul_i32 s0, s47, s36
	s_add_u32 s2, s0, s33
	s_addc_u32 s3, s1, s54
	v_cmp_gt_i64_e32 vcc, s[2:3], v[142:143]
	v_cmp_lt_i64_e64 s[0:1], s[2:3], v[140:141]
	s_cbranch_vccnz .LBB0_875
	s_ashr_i32 s3, s2, 31
	s_lshr_b32 s3, s3, 29
	s_add_i32 s3, s2, s3
	s_ashr_i32 s24, s3, 3
	s_and_b32 s3, s3, -8
	s_sub_i32 s2, s2, s3
	s_cmp_lt_i32 s2, 0
	s_cselect_b32 s3, s55, 0x80
	s_mul_i32 s2, s3, s2
	s_add_i32 s2, s2, s24
	s_ashr_i32 s3, s2, 31
	s_lshr_b32 s3, s3, 27
	s_add_i32 s3, s2, s3
	s_ashr_i32 s24, s3, 5
	s_lshl_b32 s24, s24, 3
	s_sub_i32 s25, 0x100, s24
	s_min_i32 s25, s25, 8
	s_abs_i32 s26, s25
	v_cvt_f32_u32_e32 v0, s26
	s_sub_i32 s35, 0, s26
	s_andn2_b32 s3, s3, 31
	s_sub_i32 s2, s2, s3
	v_rcp_iflag_f32_e32 v0, v0
	s_abs_i32 s3, s2
	s_xor_b32 s27, s2, s25
	s_ashr_i32 s27, s27, 31
	v_mul_f32_e32 v0, 0x4f7ffffe, v0
	v_cvt_u32_f32_e32 v0, v0
	s_nop 0
	v_readfirstlane_b32 s58, v0
	s_mul_i32 s35, s35, s58
	s_mul_hi_u32 s35, s58, s35
	s_add_i32 s58, s58, s35
	s_mul_hi_u32 s35, s3, s58
	s_mul_i32 s58, s35, s26
	s_sub_i32 s3, s3, s58
	s_add_i32 s59, s35, 1
	s_sub_i32 s58, s3, s26
	s_cmp_ge_u32 s3, s26
	s_cselect_b32 s35, s59, s35
	s_cselect_b32 s3, s58, s3
	s_add_i32 s58, s35, 1
	s_cmp_ge_u32 s3, s26
	s_cselect_b32 s3, s58, s35
	s_xor_b32 s3, s3, s27
	s_sub_i32 s58, s3, s27
	s_mul_i32 s3, s58, s25
	s_sub_i32 s2, s2, s3
	s_add_i32 s59, s2, s24

; __device__ __forceinline__ unsigned xb_ld(unsigned* p)              { return __hip_atomic_load(p, __ATOMIC_RELAXED, __HIP_MEMORY_SCOPE_AGENT); }
; __device__ __forceinline__ unsigned xb_add(unsigned* p, unsigned v) { return __hip_atomic_fetch_add(p, v, __ATOMIC_RELAXED, __HIP_MEMORY_SCOPE_AGENT); }
; #define XB_SPIN(cond, bar) do { unsigned _sp = 0; while (cond) { __builtin_amdgcn_s_sleep(1); \
;     if ((++_sp & 255u) == 0u) { if (xb_ld(&(bar)[XB_TMO])) break; if (_sp > XB_SPIN_CAP) { atomicAdd(&(bar)[XB_TMO], 1u); break; } } } } while (0)
; __device__ __forceinline__ void xcd_barrier(const XcdBarrier& b) {
;     asm volatile("s_waitcnt vmcnt(0)" ::: "memory");
;     __syncthreads();
;     if (threadIdx.x == 0) {
;         unsigned* bar = b.bar;
;         __builtin_amdgcn_s_waitcnt(0);
;         unsigned nloc = b.st[0], nx = b.st[1];
;         if (nloc == 0u) { xcd_barrier_complete(bar, b.x, nloc, nx); b.st[0] = nloc; b.st[1] = nx; }
;         const unsigned old = xb_add(&bar[XB_XSUB(b.x)], 1u);
;         const unsigned gen = old / nloc;
;         if (old + 1u == (gen + 1u) * nloc) {
;             __builtin_amdgcn_fence(__ATOMIC_RELEASE, "agent");
;             asm volatile("s_waitcnt vmcnt(0)" ::: "memory");
;             const unsigned og = xb_add(&bar[XB_TOP], 1u);
;             const unsigned tg = og / nx;
;             if (og + 1u == (tg + 1u) * nx) xb_add(&bar[XB_TOPGEN], 1u);
;             else XB_SPIN(xb_ld(&bar[XB_TOPGEN]) == tg, bar);
;             __builtin_amdgcn_fence(__ATOMIC_ACQUIRE, "agent");
;             xb_add(&bar[XB_XGEN(b.x)], 1u);
;             asm volatile("s_waitcnt vmcnt(0)" ::: "memory");
;         } else {
;             XB_SPIN(xb_ld(&bar[XB_XGEN(b.x)]) == gen, bar);
;             __builtin_amdgcn_fence(__ATOMIC_ACQUIRE, "agent");
;             asm volatile("s_waitcnt vmcnt(0)" ::: "memory");
;         }
;     }
;     __syncthreads();
.LBB0_907:
	s_cmp_gt_i32 s95, 8
	s_cselect_b64 s[0:1], -1, 0
	s_and_b64 s[2:3], s[4:5], s[0:1]
	s_andn2_b64 vcc, exec, s[2:3]
	s_cbranch_vccnz .LBB0_952
	v_readfirstlane_b32 vcc_lo, v251
	s_cmp_lg_u32 vcc_lo, 0
	s_cbranch_scc1 .LBB0_952
	s_waitcnt vmcnt(0)
	s_waitcnt vmcnt(0) lgkmcnt(0)
	s_barrier
	s_mov_b64 s[2:3], exec
	v_readlane_b32 s4, v250, 0
	v_readlane_b32 s5, v250, 1
	s_and_b64 s[4:5], s[2:3], s[4:5]
	s_mov_b64 exec, s[4:5]
	s_cbranch_execz .LBB0_951
	s_add_i32 s4, 0, 0x23fc0
	v_mov_b32_e32 v0, s4
	s_waitcnt vmcnt(0) expcnt(0) lgkmcnt(0)
	ds_read_b32 v2, v0
	s_add_i32 s4, 0, 0x23fc4
	v_mov_b32_e32 v0, s4
	ds_read_b32 v0, v0
	s_waitcnt lgkmcnt(1)
	v_cmp_ne_u32_e32 vcc, 0, v2
	s_cbranch_vccnz .LBB0_922
	s_add_u32 s4, s72, 0x1000
	s_addc_u32 s5, s73, 0
	s_add_u32 s6, s72, 0x1100
	s_addc_u32 s7, s73, 0
	s_add_u32 s8, s72, 0x1200
	s_addc_u32 s9, s73, 0
	s_mul_i32 s18, s97, s71
	s_add_u32 s10, s72, 0x1300
	s_mul_i32 s18, s18, s96
	s_addc_u32 s11, s73, 0
	s_mov_b32 s19, 1
	v_mov_b32_e32 v16, 0
	s_branch .LBB0_912

; __device__ __forceinline__ void nr_pass(bf16* X, const bf16* Y, const float* SSQ, float* ssqX, const float* g, float* out  , int gw, int NGW, int lane) {
;     f32x4 gv[4];
; #pragma unroll
;     for (int j = 0; j < 4; ++j) gv[j] = *((const f32x4*)g + lane + 64 * j);
;     for (int r = gw; r < M_REAL; r += NGW) {
;         const float part = SSQ[(size_t)r * 32 + (lane & 31)];
;         const float s = rsqrtf(half_sum32(part) * (1.0f / 1024.0f) + EPS);
;         v2u* x8 = (v2u*)(X + (size_t)r * 1024) + lane; const v2u* y8 = (const v2u*)(Y + (size_t)r * 1024) + lane;
.LBB0_952:
	v_readfirstlane_b32 vcc_lo, v251
	v_mov_b32_e32 v251, 1
	s_cmp_eq_u32 vcc_lo, 0
	s_cbranch_scc1 .Lre_p7l0
	s_cmp_lt_i32 s94, 9
	s_cselect_b64 s[2:3], -1, 0
	s_and_b64 s[0:1], s[2:3], s[0:1]
	s_andn2_b64 vcc, exec, s[0:1]
	s_cbranch_vccnz .LBB0_958
	s_mov_b64 s[4:5], s[92:93]
	s_mov_b64 s[0:1], s[90:91]
	v_mov_b32_e32 v16, v182
	v_readfirstlane_b32 s0, v183
	s_lshr_b32 s0, s0, 6
	s_mov_b32 s1, s70
	s_mov_b32 s6, s96
	s_lshl_b32 s1, s1, 3
	s_mov_b32 s63, 0x10120
	s_cmp_lt_u32 s70, 8
	s_cbranch_scc1 .Lnr_tail_p7l0
	s_sub_i32 s1, s1, 64
	s_sub_i32 s6, s6, 8
	s_mov_b32 s63, 0x10000
	s_branch .Lnr_go_p7l0
.Lnr_tail_p7l0:
	s_waitcnt vmcnt(0) lgkmcnt(0)
	s_barrier
	s_cmp_lg_u32 s0, 0
	s_cbranch_scc1 .Lnr_tsd_p7l0
	s_mov_b64 exec, 1
	buffer_wbl2 sc1
	s_waitcnt vmcnt(0)
	v_mov_b32_e32 v252, 0
	v_mov_b32_e32 v253, 1
	global_atomic_add v252, v253, s[92:93] offset:2304
	s_waitcnt vmcnt(0)
.Lnr_tspin_p7l0:
	global_load_dword v254, v252, s[92:93] offset:2304 sc1
	s_waitcnt vmcnt(0)
	v_readfirstlane_b32 vcc_lo, v254
	s_cmp_ge_u32 vcc_lo, 8
	s_cbranch_scc1 .Lnr_tspun_p7l0
	s_sleep 2
	s_branch .Lnr_tspin_p7l0

; __device__ __forceinline__ unsigned pk2(float lo, float hi) { return f2bf(lo) | (f2bf(hi) << 16); }
; __device__ __forceinline__ void nr_pass(bf16* X, const bf16* Y, const float* SSQ, float* ssqX, const float* g, float* out  , int gw, int NGW, int lane) {
;     f32x4 gv[4];
; #pragma unroll
;     for (int j = 0; j < 4; ++j) gv[j] = *((const f32x4*)g + lane + 64 * j);
;     for (int r = gw; r < M_REAL; r += NGW) {
;         const float part = SSQ[(size_t)r * 32 + (lane & 31)];
;         const float s = rsqrtf(half_sum32(part) * (1.0f / 1024.0f) + EPS);
;         v2u* x8 = (v2u*)(X + (size_t)r * 1024) + lane; const v2u* y8 = (const v2u*)(Y + (size_t)r * 1024) + lane;
;         f32x4 v[4]; float s2 = 0.f;
; #pragma unroll
;         for (int j = 0; j < 4; ++j) { const v2u xv = x8[64 * j], yv = __builtin_nontemporal_load(&y8[64 * j]);
;             v[j].x = bflo(xv.x) + bflo(yv.x) * s * gv[j].x; v[j].y = bfhi(xv.x) + bfhi(yv.x) * s * gv[j].y;
;             v[j].z = bflo(xv.y) + bflo(yv.y) * s * gv[j].z; v[j].w = bfhi(xv.y) + bfhi(yv.y) * s * gv[j].w;
;             s2 += (v[j].x * v[j].x + v[j].y * v[j].y) + (v[j].z * v[j].z + v[j].w * v[j].w); }
;         if (out == nullptr) {
;             s2 = wave_sum(s2);
; #pragma unroll
;             for (int j = 0; j < 4; ++j) x8[64 * j] = (v2u){pk2(v[j].x, v[j].y), pk2(v[j].z, v[j].w)};
;             if (lane == 0) ssqX[r] = s2;
;         } else {
;             int pos; size_t orow;
;             if (r < ROWS_P) { const int sq = r / L_P; pos = r - sq * L_P; orow = (size_t)sq * 2048 + (pos - 16); }
;             else { const int q = r - ROWS_P, sq = q / L_S; pos = q - sq * L_S; orow = (size_t)NSEQ_P * 2048 + (size_t)sq * 16384 + (pos - 16); }
;             if (pos >= 16) { f32x4* o = (f32x4*)(out + orow * 1024) + lane;
; #pragma unroll
;                 for (int j = 0; j < 4; ++j) o[64 * j] = v[j]; }
;         }
;     }
; }
.Lnr_go_p7l0:
	s_add_i32 s14, s1, s0
	s_cmp_ge_i32 s14, s63
	s_cbranch_scc1 .LBB0_958
	v_ashrrev_i32_e32 v17, 31, v16
	v_lshl_add_u64 v[18:19], v[16:17], 4, s[88:89]
	global_load_dwordx4 v[0:3], v[18:19], off
	s_waitcnt lgkmcnt(0)
	global_load_dwordx4 v[4:7], v[18:19], off offset:1024
	global_load_dwordx4 v[8:11], v[18:19], off offset:2048
	global_load_dwordx4 v[12:15], v[18:19], off offset:3072
	v_mbcnt_lo_u32_b32 v19, -1, 0
	v_mbcnt_hi_u32_b32 v19, -1, v19
	v_and_b32_e32 v20, 64, v19
	s_lshl_b32 s6, s6, 3
	s_ashr_i32 s7, s0, 31
	s_ashr_i32 s9, s1, 31
	v_xor_b32_e32 v21, 1, v19
	v_add_u32_e32 v20, 64, v20
	s_add_u32 s8, s0, s1
	v_xor_b32_e32 v24, 2, v19
	v_cmp_lt_i32_e64 s[0:1], v21, v20
	v_xor_b32_e32 v25, 4, v19
	v_xor_b32_e32 v26, 8, v19
	v_cndmask_b32_e64 v21, v19, v21, s[0:1]
	v_cmp_lt_i32_e64 s[0:1], v24, v20
	v_xor_b32_e32 v27, 16, v19
	s_addc_u32 s9, s7, s9
	v_cndmask_b32_e64 v29, v19, v24, s[0:1]
	v_cmp_lt_i32_e64 s[0:1], v25, v20
	v_xor_b32_e32 v28, 32, v19
	s_lshl_b64 s[10:11], s[8:9], 2
	v_cndmask_b32_e64 v30, v19, v25, s[0:1]
	v_cmp_lt_i32_e64 s[0:1], v26, v20
	s_add_u32 s19, s10, 0x3f80000
	v_and_b32_e32 v18, 31, v16
	v_cndmask_b32_e64 v31, v19, v26, s[0:1]
	v_cmp_lt_i32_e64 s[0:1], v27, v20
	s_addc_u32 s20, s11, 0
	s_lshl_b64 s[12:13], s[8:9], 7
	v_cndmask_b32_e64 v32, v19, v27, s[0:1]
	v_cmp_lt_i32_e64 s[0:1], v28, v20
	s_mov_b64 s[22:23], 0x3700000
	v_lshlrev_b32_e32 v25, 2, v29
	v_cndmask_b32_e64 v19, v19, v28, s[0:1]
	v_lshlrev_b32_e32 v29, 2, v19
	s_ashr_i32 s7, s6, 31
	s_lshl_b64 s[0:1], s[8:9], 11
	v_lshl_or_b32 v18, v18, 2, s12
	v_mov_b32_e32 v19, s13
	v_cmp_eq_u32_e32 vcc, 0, v16
	v_mov_b32_e32 v22, 0x358637bd
	s_mov_b32 s15, 0x800000
	s_brev_b32 s16, 32
	s_mov_b32 s17, 0xc100000
	s_movk_i32 s18, 0x7fff
	v_mov_b32_e32 v23, 0
	v_lshlrev_b32_e32 v24, 2, v21
	v_lshlrev_b32_e32 v26, 2, v30
	v_lshlrev_b32_e32 v27, 2, v31
	v_lshlrev_b32_e32 v28, 2, v32
	s_lshl_b64 s[8:9], s[6:7], 2
	v_lshl_add_u64 v[16:17], v[16:17], 3, s[0:1]
	s_lshl_b64 s[10:11], s[6:7], 11
	s_lshl_b64 s[12:13], s[6:7], 7
	v_lshl_add_u64 v[18:19], v[18:19], 0, s[22:23]
	v_mov_b32_e32 v30, 1
	s_waitcnt vmcnt(0)
	v_mov_b32_e32 v20, v1
	v_mov_b32_e32 v21, v3
	v_mov_b32_e32 v1, v2
	v_mov_b32_e32 v2, v5
	v_mov_b32_e32 v3, v7
	v_mov_b32_e32 v5, v6
	v_mov_b32_e32 v6, v9
	v_mov_b32_e32 v7, v11
	v_mov_b32_e32 v9, v10
	v_mov_b32_e32 v10, v13
	v_mov_b32_e32 v11, v15
	v_mov_b32_e32 v13, v14
	s_branch .LBB0_956
.LBB0_955:
	s_or_b64 exec, exec, s[0:1]
	s_add_i32 s14, s14, s6
	s_add_u32 s19, s19, s8
	s_addc_u32 s20, s20, s9
	v_lshl_add_u64 v[16:17], v[16:17], 0, s[10:11]
	s_cmp_lt_i32 s14, s63
	v_lshl_add_u64 v[18:19], v[18:19], 0, s[12:13]
	s_cbranch_scc0 .LBB0_958

; #define PG8_LAS __attribute__((address_space(3)))
;     __host__ __device__ bool next(int i, Unit& u) const {
;         const long L = (long)i * G + c; if (L >= nwg) return false;
;         int wgid = (int)L; { const int q = nwg / NXCD, r = nwg % NXCD, xcd = wgid % NXCD, off = wgid / NXCD; wgid = (xcd < r ? xcd * (q + 1) : r * (q + 1) + (xcd - r) * q) + off; }
;         const int nig = WGM * nN, gid = wgid / nig, fm = gid * WGM, gsz = (nM - fm) < WGM ? (nM - fm) : WGM;
;         u.pm = fm + ((wgid % nig) % gsz); u.pn = (wgid % nig) / gsz; return true;
; template <class Epi, class Sched, bool ALIGN_EPI = false, bool SP2 = false>
; __device__ __forceinline__ void gemm_phase(PG8_LAS unsigned char* lds, const Gemm g, const Sched& S, const Epi& E) {
;     int tid = threadIdx.x; asm volatile("" : "+v"(tid));
;     const int wid = __builtin_amdgcn_readfirstlane(tid >> 6), lane = tid & 63, wr = wid >> 2, wc = wid & 3, fr = lane & 15, fq = lane >> 4;
;     int K = g.K; asm volatile("" : "+s"(K));
;     const int nt = K / BK;
;     unsigned voffA[2], voffB[2];
.LBB0_1457:
	v_mov_b32_e32 v251, 0
	s_cmp_lt_i32 s94, 13
	s_cselect_b64 s[8:9], -1, 0
	s_and_b64 s[0:1], s[8:9], s[0:1]
	s_andn2_b64 vcc, exec, s[0:1]
	s_cbranch_vccnz .LBB0_1495
.Lre_p4l1:
	v_readfirstlane_b32 s0, v183
	s_mov_b64 s[4:5], s[92:93]
	s_mov_b64 s[10:11], s[90:91]
	s_lshr_b32 s0, s0, 6
	v_mov_b32_e32 v0, v182
	s_mov_b32 s33, s96
	s_mov_b32 s36, s70
	v_readfirstlane_b32 vcc_lo, v251
	s_cmp_eq_u32 vcc_lo, 0
	s_cbranch_scc1 .Lm0_p4l1
	s_addk_i32 s36, 0x3f8
	s_mov_b32 s33, 0x10000

; #define PG8_WAIT_V(n) asm volatile("s_waitcnt vmcnt(" #n ")" ::: "memory")
; template <class Epi, class Sched, bool ALIGN_EPI = false, bool SP2 = false>
; __device__ __forceinline__ void gemm_phase(PG8_LAS unsigned char* lds, const Gemm g, const Sched& S, const Epi& E) {
;     ...
; #pragma unroll
;     for (int i = 0; i < 2; ++i) { int R, C; stage_rc(tid * 16 + i * 8192, R, C); const int Rb = Epi::PERM ? ((R & ~31) + perm32(R & 31)) : R;
;         voffA[i] = (unsigned)(R * g.lda + C) * 2u; voffB[i] = (unsigned)(Rb * K + C) * 2u; }
;     const size_t kstep = (size_t)(BK * 2);
;     const size_t hstepA = (size_t)HALF * g.lda * 2, hstepB = (size_t)HALF * K * 2;
;     const size_t tstepA = 2 * hstepA, tstepB = 2 * hstepB;
;     const unsigned ldsw = (unsigned)wid * 1024u;
;     const int aoff = lds_byte(wr * 64 + fr, fq * 8), boff = lds_byte(wc * 32 + fr, fq * 8);
;     ...
;     Unit cur, nxt; int ui = 0;
;     if (!S.next(0, cur)) return;
;     f32x4 acc[2][2][4][2];
; #pragma unroll
;     for (int a = 0; a < 2; ++a)
; #pragma unroll
;         for (int b = 0; b < 2; ++b)
; #pragma unroll
;             for (int m = 0; m < 4; ++m)
; #pragma unroll
;                 for (int n = 0; n < 2; ++n) acc[a][b][m][n] = (f32x4){0.f, 0.f, 0.f, 0.f};
;     bf16x8 At[4][2], B0[2][2], B1[2][2];
;     const char* cA = (cur.pm < g.pm_split) ? (const char*)g.A + (size_t)cur.pm * tstepA : (const char*)g.A2 + (size_t)(cur.pm - g.pm_split) * tstepA; const char* cB = (const char*)g.Bt + (size_t)cur.pn * tstepB;
;     S.a_ready(cur);
;     if constexpr (SP2) {
;         PG8_STAGE(PG8_SB(0, 0), cB, voffB); PG8_STAGE(PG8_SB(0, 1), cB + hstepB, voffB); PG8_STAGE(PG8_SA(0, 0), cA, voffA); PG8_STAGE(PG8_SA(0, 1), cA + hstepA, voffA);
;         if (wr == 1) PG8_BAR;
;         PG8_WAIT_V(2); PG8_BAR;
;         PG8_STAGE(PG8_SB(1, 0), cB + kstep, voffB); PG8_STAGE(PG8_SA(1, 0), cA + kstep, voffA); PG8_STAGE(PG8_SB(1, 1), cB + hstepB + kstep, voffB);
;         PG8_WAIT_V(6); PG8_BAR;
;     } else {
;         PG8_STAGE(PG8_SB(0, 0), cB, voffB); PG8_STAGE(PG8_SA(0, 0), cA, voffA); PG8_STAGE(PG8_SB(0, 1), cB + hstepB, voffB); PG8_STAGE(PG8_SA(0, 1), cA + hstepA, voffA);
;         if (wr == 1) PG8_BAR;
;         PG8_WAIT_V(4); PG8_BAR;
;         PG8_STAGE(PG8_SB(1, 0), cB + kstep, voffB); PG8_STAGE(PG8_SA(1, 0), cA + kstep, voffA); PG8_STAGE(PG8_SB(1, 1), cB + hstepB + kstep, voffB);
.Lm1_p4l1:
	v_ashrrev_i32_e32 v1, 31, v12
	v_lshrrev_b32_e32 v1, 26, v1
	v_add_u32_e32 v1, v12, v1
	v_ashrrev_i32_e32 v13, 6, v1
	v_bfe_i32 v1, v12, 27, 1
	v_lshlrev_b32_e32 v0, 4, v12
	v_lshrrev_b32_e32 v1, 22, v1
	v_add_u32_e32 v1, v0, v1
	v_and_b32_e32 v1, 0xfffffc00, v1
	v_sub_u32_e32 v1, v0, v1
	v_lshrrev_b32_e32 v2, 4, v1
	v_bitop3_b32 v1, v2, v1, 32 bitop3:0x6c
	v_ashrrev_i32_e32 v3, 31, v1
	v_lshrrev_b32_e32 v3, 26, v3
	v_add_u32_e32 v3, v1, v3
	v_ashrrev_i32_e32 v14, 6, v3
	v_and_b32_e32 v3, 0xc0, v3
	v_lshlrev_b32_e32 v2, 3, v13
	v_sub_u32_e32 v1, v1, v3
	v_mov_b32_e32 v3, 1
	v_and_b32_e32 v2, -16, v2
	s_waitcnt lgkmcnt(0)
	v_lshlrev_b32_e32 v4, 5, v13
	v_ashrrev_i16_sdwa v1, v3, sext(v1) dst_sel:DWORD dst_unused:UNUSED_PAD src0_sel:DWORD src1_sel:BYTE_0
	v_add_u32_e32 v2, v14, v2
	v_and_b32_e32 v4, 32, v4
	v_bfe_i32 v15, v1, 0, 16
	v_add_u32_e32 v1, v4, v15
	v_lshlrev_b32_e32 v4, 1, v2
	v_lshrrev_b32_e32 v5, 2, v2
	v_and_b32_e32 v6, 3, v14
	s_mov_b32 s1, 0x7fffffe0
	v_and_b32_e32 v4, 24, v4
	v_and_b32_e32 v5, 4, v5
	v_and_or_b32 v6, v2, s1, v6
	v_or3_b32 v4, v6, v5, v4
	v_lshlrev_b32_e32 v2, 11, v2
	v_lshl_add_u32 v128, v1, 1, v2
	v_mul_lo_u32 v2, v4, s2
	v_add_u32_e32 v0, 0x2000, v0
	v_add_lshl_u32 v130, v2, v1, 1
	v_ashrrev_i32_e32 v1, 31, v0
	v_lshrrev_b32_e32 v1, 22, v1
	v_add_u32_e32 v1, v0, v1
	v_ashrrev_i32_e32 v16, 10, v1
	v_mul_i32_i24_e32 v1, 0x400, v16
	v_sub_u32_e32 v0, v0, v1
	v_lshrrev_b32_e32 v1, 4, v0
	v_bitop3_b32 v0, v1, v0, 32 bitop3:0x6c
	v_ashrrev_i32_e32 v2, 31, v0
	v_lshrrev_b32_e32 v2, 26, v2
	v_add_u32_e32 v2, v0, v2
	v_ashrrev_i32_e32 v17, 6, v2
	v_and_b32_e32 v2, 0xc0, v2
	v_sub_u32_e32 v0, v0, v2
	s_add_u32 s37, s4, 0x14200000
	v_lshlrev_b32_e32 v1, 3, v16
	v_lshlrev_b32_e32 v4, 5, v16
	v_ashrrev_i16_sdwa v0, v3, sext(v0) dst_sel:DWORD dst_unused:UNUSED_PAD src0_sel:DWORD src1_sel:BYTE_0
	s_addc_u32 s38, s5, 0
	v_and_b32_e32 v1, -16, v1
	v_and_b32_e32 v4, 32, v4
	v_bfe_i32 v18, v0, 0, 16
	s_add_u32 s39, s4, 0x1ea0000
	v_add_u32_e32 v1, v17, v1
	v_add_u32_e32 v0, v4, v18
	v_and_b32_e32 v4, 3, v17
	s_addc_u32 s40, s5, 0
	s_ashr_i32 s6, s22, 6
	v_and_or_b32 v4, v1, s1, v4
	s_ashr_i32 s3, s2, 31
	s_ashr_i32 s1, s0, 31
	s_ashr_i32 s41, s22, 8
	s_lshl_b64 s[12:13], s[2:3], 8
	s_lshl_b64 s[14:15], s[2:3], 9
	s_lshl_b32 s42, s6, 10
	s_lshl_b64 s[16:17], s[0:1], 19
	s_add_u32 s30, s37, s16
	s_addc_u32 s31, s38, s17
	s_ashr_i32 s1, s59, 31
	s_mul_i32 s1, s14, s1
	s_mul_hi_u32 s7, s14, s59
	s_lshr_b64 s[16:17], s[2:3], 23
	s_add_i32 s1, s7, s1
	s_mul_i32 s7, s16, s59
	s_add_i32 s1, s1, s7
	s_mul_i32 s7, s14, s59
	v_lshlrev_b32_e32 v2, 1, v1
	v_lshrrev_b32_e32 v3, 2, v1
	s_add_u32 s34, s39, s7
	v_and_b32_e32 v2, 24, v2
	v_and_b32_e32 v3, 4, v3
	s_addc_u32 s35, s40, s1
	s_add_i32 s43, s42, 0
	v_or3_b32 v2, v4, v3, v2
	v_lshlrev_b32_e32 v1, 11, v1
	s_add_i32 m0, s43, 0x10000
	v_lshl_add_u32 v132, v0, 1, v1
	v_mul_lo_u32 v1, v2, s2
	global_load_lds_dwordx4 v130, s[34:35]
	s_add_i32 m0, s43, 0x12000
	v_add_lshl_u32 v134, v1, v0, 1
	s_add_u32 s16, s34, s12
	global_load_lds_dwordx4 v134, s[34:35]
	s_addc_u32 s17, s35, s13
	s_add_i32 m0, s43, 0x14000
	s_add_i32 s44, s43, 0x2000
	global_load_lds_dwordx4 v130, s[16:17]
	s_add_i32 m0, s43, 0x16000
	s_add_u32 s18, s30, 0x40000
	global_load_lds_dwordx4 v134, s[16:17]
	s_mov_b32 m0, s43
	s_addc_u32 s19, s31, 0
	global_load_lds_dwordx4 v128, s[30:31]
	s_mov_b32 m0, s44
	s_add_i32 s45, s43, 0x4000
	global_load_lds_dwordx4 v132, s[30:31]
	s_mov_b32 m0, s45
	s_add_i32 s46, s43, 0x6000
	global_load_lds_dwordx4 v128, s[18:19]
	s_mov_b32 m0, s46
	v_mov_b32_e32 v131, 0
	global_load_lds_dwordx4 v132, s[18:19]
	v_mov_b32_e32 v135, v131
	v_mov_b32_e32 v129, v131
	v_mov_b32_e32 v133, v131
	s_cmp_eq_u32 s41, 1
	s_mov_b32 s47, 0
	v_lshl_add_u64 v[8:9], s[34:35], 0, v[130:131]
	v_lshl_add_u64 v[4:5], s[34:35], 0, v[134:135]
	v_lshl_add_u64 v[2:3], s[16:17], 0, v[130:131]
	v_lshl_add_u64 v[0:1], s[16:17], 0, v[134:135]
	v_lshl_add_u64 v[6:7], s[30:31], 0, v[128:129]
	s_cselect_b64 s[16:17], -1, 0
	s_cmp_lg_u32 s41, 1
	v_lshl_add_u64 v[10:11], s[30:31], 0, v[132:133]
	s_cbranch_scc1 .LBB0_1463
	s_barrier

; __device__ __forceinline__ unsigned xb_ld(unsigned* p)              { return __hip_atomic_load(p, __ATOMIC_RELAXED, __HIP_MEMORY_SCOPE_AGENT); }
; __device__ __forceinline__ unsigned xb_add(unsigned* p, unsigned v) { return __hip_atomic_fetch_add(p, v, __ATOMIC_RELAXED, __HIP_MEMORY_SCOPE_AGENT); }
; #define XB_SPIN(cond, bar) do { unsigned _sp = 0; while (cond) { __builtin_amdgcn_s_sleep(1); \
;     if ((++_sp & 255u) == 0u) { if (xb_ld(&(bar)[XB_TMO])) break; if (_sp > XB_SPIN_CAP) { atomicAdd(&(bar)[XB_TMO], 1u); break; } } } } while (0)
; __device__ __forceinline__ void xcd_barrier(const XcdBarrier& b) {
;     asm volatile("s_waitcnt vmcnt(0)" ::: "memory");
;     __syncthreads();
;     if (threadIdx.x == 0) {
;         unsigned* bar = b.bar;
;         __builtin_amdgcn_s_waitcnt(0);
;         unsigned nloc = b.st[0], nx = b.st[1];
;         if (nloc == 0u) { xcd_barrier_complete(bar, b.x, nloc, nx); b.st[0] = nloc; b.st[1] = nx; }
;         const unsigned old = xb_add(&bar[XB_XSUB(b.x)], 1u);
;         const unsigned gen = old / nloc;
;         if (old + 1u == (gen + 1u) * nloc) {
;             __builtin_amdgcn_fence(__ATOMIC_RELEASE, "agent");
;             asm volatile("s_waitcnt vmcnt(0)" ::: "memory");
;             const unsigned og = xb_add(&bar[XB_TOP], 1u);
;             const unsigned tg = og / nx;
;             if (og + 1u == (tg + 1u) * nx) xb_add(&bar[XB_TOPGEN], 1u);
;             else XB_SPIN(xb_ld(&bar[XB_TOPGEN]) == tg, bar);
;             __builtin_amdgcn_fence(__ATOMIC_ACQUIRE, "agent");
;             xb_add(&bar[XB_XGEN(b.x)], 1u);
;             asm volatile("s_waitcnt vmcnt(0)" ::: "memory");
;         } else {
;             XB_SPIN(xb_ld(&bar[XB_XGEN(b.x)]) == gen, bar);
;             __builtin_amdgcn_fence(__ATOMIC_ACQUIRE, "agent");
;             asm volatile("s_waitcnt vmcnt(0)" ::: "memory");
;         }
;     }
;     __syncthreads();
.LBB0_1495:
	s_cmp_gt_i32 s95, 13
	s_cselect_b64 s[0:1], -1, 0
	s_and_b64 s[2:3], s[8:9], s[0:1]
	s_andn2_b64 vcc, exec, s[2:3]
	s_cbranch_vccnz .LBB0_1540
	v_readfirstlane_b32 vcc_lo, v251
	s_cmp_lg_u32 vcc_lo, 0
	s_cbranch_scc1 .LBB0_1540
	s_waitcnt vmcnt(0)
	s_waitcnt vmcnt(0) lgkmcnt(0)
	s_barrier
	s_mov_b64 s[2:3], exec
	v_readlane_b32 s4, v250, 0
	v_readlane_b32 s5, v250, 1
	s_and_b64 s[4:5], s[2:3], s[4:5]
	s_mov_b64 exec, s[4:5]
	s_cbranch_execz .LBB0_1539
	s_add_i32 s4, 0, 0x23fc0
	v_mov_b32_e32 v0, s4
	s_waitcnt vmcnt(0) expcnt(0) lgkmcnt(0)
	ds_read_b32 v2, v0
	s_add_i32 s4, 0, 0x23fc4
	v_mov_b32_e32 v0, s4
	ds_read_b32 v0, v0
	s_waitcnt lgkmcnt(1)
	v_cmp_ne_u32_e32 vcc, 0, v2
	s_cbranch_vccnz .LBB0_1510
	s_add_u32 s4, s72, 0x1000
	s_addc_u32 s5, s73, 0
	s_add_u32 s6, s72, 0x1100
	s_addc_u32 s7, s73, 0
	s_add_u32 s8, s72, 0x1200
	s_addc_u32 s9, s73, 0
	s_mul_i32 s18, s97, s71
	s_add_u32 s10, s72, 0x1300
	s_mul_i32 s18, s18, s96
	s_addc_u32 s11, s73, 0
	s_mov_b32 s19, 1
	v_mov_b32_e32 v16, 0
	s_branch .LBB0_1500

; __device__ __forceinline__ void nr_pass(bf16* X, const bf16* Y, const float* SSQ, float* ssqX, const float* g, float* out  , int gw, int NGW, int lane) {
;     f32x4 gv[4];
; #pragma unroll
;     for (int j = 0; j < 4; ++j) gv[j] = *((const f32x4*)g + lane + 64 * j);
;     for (int r = gw; r < M_REAL; r += NGW) {
;         const float part = SSQ[(size_t)r * 32 + (lane & 31)];
;         const float s = rsqrtf(half_sum32(part) * (1.0f / 1024.0f) + EPS);
;         v2u* x8 = (v2u*)(X + (size_t)r * 1024) + lane; const v2u* y8 = (const v2u*)(Y + (size_t)r * 1024) + lane;
.LBB0_1540:
	v_readfirstlane_b32 vcc_lo, v251
	v_mov_b32_e32 v251, 1
	s_cmp_eq_u32 vcc_lo, 0
	s_cbranch_scc1 .Lre_p4l1
	s_cmp_lt_i32 s94, 14
	s_cselect_b64 s[4:5], -1, 0
	s_and_b64 s[0:1], s[4:5], s[0:1]
	s_andn2_b64 vcc, exec, s[0:1]
	s_cbranch_vccnz .LBB0_1546
	v_readfirstlane_b32 s0, v183
	s_mov_b64 s[2:3], s[90:91]
	s_mov_b64 s[14:15], s[92:93]
	s_lshr_b32 s0, s0, 6
	s_waitcnt lgkmcnt(0)
	v_mov_b32_e32 v20, v182
	s_mov_b32 s6, s96
	s_mov_b32 s1, s70
	s_lshl_b32 s1, s1, 3
	s_mov_b32 s63, 0x10120
	s_cmp_lt_u32 s70, 8
	s_cbranch_scc1 .Lnr_tail_p4l1
	s_sub_i32 s1, s1, 64
	s_sub_i32 s6, s6, 8
	s_mov_b32 s63, 0x10000
	s_branch .Lnr_go_p4l1
.Lnr_tail_p4l1:
	s_waitcnt vmcnt(0) lgkmcnt(0)
	s_barrier
	s_cmp_lg_u32 s0, 0
	s_cbranch_scc1 .Lnr_tsd_p4l1
	s_mov_b64 exec, 1
	buffer_wbl2 sc1
	s_waitcnt vmcnt(0)
	v_mov_b32_e32 v252, 0
	v_mov_b32_e32 v253, 1
	global_atomic_add v252, v253, s[92:93] offset:2560
	s_waitcnt vmcnt(0)
.Lnr_tspin_p4l1:
	global_load_dword v254, v252, s[92:93] offset:2560 sc1
	s_waitcnt vmcnt(0)
	v_readfirstlane_b32 vcc_lo, v254
	s_cmp_ge_u32 vcc_lo, 8
	s_cbranch_scc1 .Lnr_tspun_p4l1
	s_sleep 2
	s_branch .Lnr_tspin_p4l1

; __device__ __forceinline__ unsigned pk2(float lo, float hi) { return f2bf(lo) | (f2bf(hi) << 16); }
; __device__ __forceinline__ void nr_pass(bf16* X, const bf16* Y, const float* SSQ, float* ssqX, const float* g, float* out  , int gw, int NGW, int lane) {
;     f32x4 gv[4];
; #pragma unroll
;     for (int j = 0; j < 4; ++j) gv[j] = *((const f32x4*)g + lane + 64 * j);
;     for (int r = gw; r < M_REAL; r += NGW) {
;         const float part = SSQ[(size_t)r * 32 + (lane & 31)];
;         const float s = rsqrtf(half_sum32(part) * (1.0f / 1024.0f) + EPS);
;         v2u* x8 = (v2u*)(X + (size_t)r * 1024) + lane; const v2u* y8 = (const v2u*)(Y + (size_t)r * 1024) + lane;
;         f32x4 v[4]; float s2 = 0.f;
; #pragma unroll
;         for (int j = 0; j < 4; ++j) { const v2u xv = x8[64 * j], yv = __builtin_nontemporal_load(&y8[64 * j]);
;             v[j].x = bflo(xv.x) + bflo(yv.x) * s * gv[j].x; v[j].y = bfhi(xv.x) + bfhi(yv.x) * s * gv[j].y;
;             v[j].z = bflo(xv.y) + bflo(yv.y) * s * gv[j].z; v[j].w = bfhi(xv.y) + bfhi(yv.y) * s * gv[j].w;
;             s2 += (v[j].x * v[j].x + v[j].y * v[j].y) + (v[j].z * v[j].z + v[j].w * v[j].w); }
;         if (out == nullptr) {
;             s2 = wave_sum(s2);
; #pragma unroll
;             for (int j = 0; j < 4; ++j) x8[64 * j] = (v2u){pk2(v[j].x, v[j].y), pk2(v[j].z, v[j].w)};
;             if (lane == 0) ssqX[r] = s2;
;         } else {
;             int pos; size_t orow;
;             if (r < ROWS_P) { const int sq = r / L_P; pos = r - sq * L_P; orow = (size_t)sq * 2048 + (pos - 16); }
;             else { const int q = r - ROWS_P, sq = q / L_S; pos = q - sq * L_S; orow = (size_t)NSEQ_P * 2048 + (size_t)sq * 16384 + (pos - 16); }
;             if (pos >= 16) { f32x4* o = (f32x4*)(out + orow * 1024) + lane;
; #pragma unroll
;                 for (int j = 0; j < 4; ++j) o[64 * j] = v[j]; }
;         }
;     }
; }
.Lnr_go_p4l1:
	s_add_i32 s18, s1, s0
	s_cmp_ge_i32 s18, s63
	s_cbranch_scc1 .LBB0_1546
	v_readlane_b32 s36, v250, 2
	v_ashrrev_i32_e32 v21, 31, v20
	v_readlane_b32 s42, v250, 8
	v_readlane_b32 s43, v250, 9
	s_mov_b64 s[8:9], 0x1000
	v_mbcnt_lo_u32_b32 v18, -1, 0
	v_lshl_add_u64 v[12:13], v[20:21], 4, s[42:43]
	v_lshl_add_u64 v[14:15], v[12:13], 0, s[8:9]
	v_add_co_u32_e32 v12, vcc, 0x1000, v12
	global_load_dwordx4 v[0:3], v[14:15], off offset:1024
	global_load_dwordx4 v[4:7], v[14:15], off offset:2048
	global_load_dwordx4 v[8:11], v[14:15], off offset:3072
	v_addc_co_u32_e32 v13, vcc, 0, v13, vcc
	global_load_dwordx4 v[12:15], v[12:13], off
	v_mbcnt_hi_u32_b32 v18, -1, v18
	v_and_b32_e32 v19, 64, v18
	s_lshl_b32 s6, s6, 3
	s_ashr_i32 s7, s0, 31
	s_ashr_i32 s8, s1, 31
	v_xor_b32_e32 v22, 1, v18
	v_add_u32_e32 v19, 64, v19
	s_add_u32 s20, s0, s1
	v_xor_b32_e32 v23, 2, v18
	v_cmp_lt_i32_e64 s[0:1], v22, v19
	v_xor_b32_e32 v25, 4, v18
	v_xor_b32_e32 v26, 8, v18
	v_cndmask_b32_e64 v22, v18, v22, s[0:1]
	v_cmp_lt_i32_e64 s[0:1], v23, v19
	v_xor_b32_e32 v27, 16, v18
	v_xor_b32_e32 v28, 32, v18
	v_cndmask_b32_e64 v23, v18, v23, s[0:1]
	v_cmp_lt_i32_e64 s[0:1], v25, v19
	s_addc_u32 s21, s7, s8
	s_lshl_b64 s[8:9], s[20:21], 2
	v_cndmask_b32_e64 v29, v18, v25, s[0:1]
	v_cmp_lt_i32_e64 s[0:1], v26, v19
	v_and_b32_e32 v16, 31, v20
	v_mov_b32_e32 v17, 0
	v_cndmask_b32_e64 v30, v18, v26, s[0:1]
	v_cmp_lt_i32_e64 s[0:1], v27, v19
	v_lshlrev_b32_e32 v16, 2, v16
	s_mov_b64 s[16:17], 0x3700000
	v_cndmask_b32_e64 v31, v18, v27, s[0:1]
	v_cmp_lt_i32_e64 s[0:1], v28, v19
	v_cmp_eq_u32_e32 vcc, 0, v20
	v_mov_b32_e32 v24, 0x358637bd
	v_cndmask_b32_e64 v18, v18, v28, s[0:1]
	s_add_u32 s0, s14, s8
	s_addc_u32 s1, s15, s9
	s_add_u32 s8, s0, 0x3f80000
	s_addc_u32 s9, s1, 0
	s_ashr_i32 s7, s6, 31
	s_lshl_b64 s[0:1], s[20:21], 7
	s_lshl_b64 s[10:11], s[6:7], 2
	s_add_u32 s0, s14, s0
	s_addc_u32 s1, s15, s1
	s_lshl_b64 s[12:13], s[6:7], 7
	s_add_u32 s14, s14, 0x4000400
	v_lshlrev_b32_e32 v28, 2, v30
	v_lshlrev_b32_e32 v30, 2, v18
	v_lshl_add_u64 v[18:19], s[0:1], 0, v[16:17]
	s_addc_u32 s15, s15, 0
	s_lshl_b64 s[0:1], s[20:21], 11
	s_mov_b32 s19, 0x800000
	v_lshlrev_b32_e32 v25, 2, v22
	v_lshlrev_b32_e32 v26, 2, v23
	v_lshlrev_b32_e32 v27, 2, v29
	v_lshlrev_b32_e32 v29, 2, v31
	v_lshl_add_u64 v[18:19], v[18:19], 0, s[16:17]
	s_lshl_b64 s[16:17], s[6:7], 11
	v_lshl_add_u64 v[20:21], v[20:21], 3, s[0:1]
	s_movk_i32 s7, 0x7fff
	v_mov_b32_e32 v16, 1
	v_readlane_b32 s37, v250, 3
	v_readlane_b32 s38, v250, 4
	v_readlane_b32 s39, v250, 5
	v_readlane_b32 s40, v250, 6
	v_readlane_b32 s41, v250, 7
	v_readlane_b32 s44, v250, 10
	v_readlane_b32 s45, v250, 11
	v_readlane_b32 s46, v250, 12
	v_readlane_b32 s47, v250, 13
	v_readlane_b32 s48, v250, 14
	v_readlane_b32 s49, v250, 15
	v_readlane_b32 s50, v250, 16
	v_readlane_b32 s51, v250, 17
	s_waitcnt vmcnt(0)
	v_mov_b32_e32 v22, v1
	v_mov_b32_e32 v23, v3
	v_mov_b32_e32 v1, v2
	v_mov_b32_e32 v2, v5
	v_mov_b32_e32 v3, v7
	v_mov_b32_e32 v5, v6
	v_mov_b32_e32 v6, v9
	v_mov_b32_e32 v7, v11
	v_mov_b32_e32 v9, v10
	v_mov_b32_e32 v10, v13
	v_mov_b32_e32 v11, v15
	v_mov_b32_e32 v13, v14
	s_branch .LBB0_1544

; __global__ void __launch_bounds__(NWAVES * 64, 2) mega_fwd(Args a) {
;     extern __shared__ __attribute__((aligned(16))) unsigned char lds[];
	.amdhsa_kernel _Z8mega_fwd4Args
		.amdhsa_group_segment_fixed_size 0
		.amdhsa_private_segment_fixed_size 0
		.amdhsa_kernarg_size 416
		.amdhsa_user_sgpr_count 2
		.amdhsa_user_sgpr_dispatch_ptr 0
		.amdhsa_user_sgpr_queue_ptr 0
		.amdhsa_user_sgpr_kernarg_segment_ptr 1
		.amdhsa_user_sgpr_dispatch_id 0
		.amdhsa_user_sgpr_kernarg_preload_length 0
		.amdhsa_user_sgpr_kernarg_preload_offset 0
		.amdhsa_user_sgpr_private_segment_size 0
		.amdhsa_uses_dynamic_stack 0
		.amdhsa_enable_private_segment 0
		.amdhsa_system_sgpr_workgroup_id_x 1
		.amdhsa_system_sgpr_workgroup_id_y 0
		.amdhsa_system_sgpr_workgroup_id_z 0
		.amdhsa_system_sgpr_workgroup_info 0
		.amdhsa_system_vgpr_workitem_id 2
		.amdhsa_next_free_vgpr 256
		.amdhsa_next_free_sgpr 98
		.amdhsa_accum_offset 256
		.amdhsa_reserve_vcc 1
		.amdhsa_float_round_mode_32 0
		.amdhsa_float_round_mode_16_64 0
		.amdhsa_float_denorm_mode_32 3
		.amdhsa_float_denorm_mode_16_64 3
		.amdhsa_dx10_clamp 1
		.amdhsa_ieee_mode 1
		.amdhsa_fp16_overflow 0
		.amdhsa_tg_split 0
		.amdhsa_exception_fp_ieee_invalid_op 0
		.amdhsa_exception_fp_denorm_src 0
		.amdhsa_exception_fp_ieee_div_zero 0
		.amdhsa_exception_fp_ieee_overflow 0
		.amdhsa_exception_fp_ieee_underflow 0
		.amdhsa_exception_fp_ieee_inexact 0
		.amdhsa_exception_int_div_zero 0
	.end_amdhsa_kernel

; __global__ void __launch_bounds__(NWAVES * 64, 2) mega_fwd(Args a) {
;     extern __shared__ __attribute__((aligned(16))) unsigned char lds[];
amdhsa.kernels:
  - .agpr_count:     0
    .args:
      - .offset:         0
        .size:           160
        .value_kind:     by_value
      - .offset:         160
        .size:           4
        .value_kind:     hidden_block_count_x
      - .offset:         164
        .size:           4
        .value_kind:     hidden_block_count_y
      - .offset:         168
        .size:           4
        .value_kind:     hidden_block_count_z
      - .offset:         172
        .size:           2
        .value_kind:     hidden_group_size_x
      - .offset:         174
        .size:           2
        .value_kind:     hidden_group_size_y
      - .offset:         176
        .size:           2
        .value_kind:     hidden_group_size_z
      - .offset:         178
        .size:           2
        .value_kind:     hidden_remainder_x
      - .offset:         180
        .size:           2
        .value_kind:     hidden_remainder_y
      - .offset:         182
        .size:           2
        .value_kind:     hidden_remainder_z
      - .offset:         200
        .size:           8
        .value_kind:     hidden_global_offset_x
      - .offset:         208
        .size:           8
        .value_kind:     hidden_global_offset_y
      - .offset:         216
        .size:           8
        .value_kind:     hidden_global_offset_z
      - .offset:         224
        .size:           2
        .value_kind:     hidden_grid_dims
      - .offset:         248
        .size:           8
        .value_kind:     hidden_multigrid_sync_arg
      - .offset:         280
        .size:           4
        .value_kind:     hidden_dynamic_lds_size
    .group_segment_fixed_size: 0
    .kernarg_segment_align: 8
    .kernarg_segment_size: 416
    .language:       OpenCL C
    .language_version:
      - 2
      - 0
    .max_flat_workgroup_size: 512
    .name:           _Z8mega_fwd4Args
    .private_segment_fixed_size: 0
    .sgpr_count:     104
    .sgpr_spill_count: 79
    .symbol:         _Z8mega_fwd4Args.kd
    .uniform_work_group_size: 1
    .uses_dynamic_stack: false
    .vgpr_count:     256
    .vgpr_spill_count: 0
    .wavefront_size: 64
